# RWKV phase: scan waves raised to priority 2 (helper waves stay at 0)
# baseline (speedup 1.0000x reference)
.LBB0_390:
	s_setprio 2
	s_and_b32 s3, s2, 1
	s_mul_i32 s8, s3, 0x5000
	v_add_u32_e32 v2, s8, v136
	s_mul_i32 s8, s2, 0xab
	s_bfe_u32 s8, s8, 0x70009
	s_mul_i32 s8, s8, 3
	s_sub_i32 s8, s2, s8
	s_and_b32 s8, s8, 0xff
	s_mulk_i32 s8, 0x1100
	v_add_u32_e32 v3, s8, v137
	v_lshl_add_u32 v1, s3, 12, v137
	ds_read_b128 v[176:179], v2 offset:4096
	ds_read_b128 v[180:183], v2 offset:4112
	ds_read_b128 v[200:203], v2 offset:12288
	ds_read_b128 v[204:207], v2 offset:12304
	ds_read_b64 v[216:217], v3 offset:40960
	ds_read_b128 v[184:187], v2 offset:0
	ds_read_b128 v[188:191], v2 offset:16
	ds_read_b128 v[192:195], v2 offset:8192
	ds_read_b128 v[196:199], v2 offset:8208
	s_waitcnt lgkmcnt(0)
	v_pk_mul_f32 v[164:165], v[72:73], v[176:177]
	v_pk_mul_f32 v[166:167], v[80:81], v[176:177]
	ds_read_b128 v[208:211], v2 offset:16384
	v_pk_fma_f32 v[164:165], v[74:75], v[178:179], v[164:165]
	v_pk_fma_f32 v[166:167], v[82:83], v[178:179], v[166:167]
	ds_read_b128 v[212:215], v2 offset:16400
	v_pk_fma_f32 v[164:165], v[76:77], v[180:181], v[164:165]
	v_pk_fma_f32 v[166:167], v[84:85], v[180:181], v[166:167]
	ds_read_b128 v[4:7], v2 offset:4352
	v_pk_fma_f32 v[164:165], v[78:79], v[182:183], v[164:165]
	v_pk_fma_f32 v[166:167], v[86:87], v[182:183], v[166:167]
	ds_read_b128 v[8:11], v2 offset:4368
	v_pk_mul_f32 v[218:219], v[216:217], v[200:201] op_sel_hi:[0,1]
	v_pk_mul_f32 v[226:227], v[216:217], v[200:201] op_sel:[1,0]
	ds_read_b128 v[40:43], v2 offset:12544
	v_pk_mul_f32 v[220:221], v[216:217], v[202:203] op_sel_hi:[0,1]
	v_pk_mul_f32 v[228:229], v[216:217], v[202:203] op_sel:[1,0]
	ds_read_b128 v[44:47], v2 offset:12560
	v_pk_mul_f32 v[222:223], v[216:217], v[204:205] op_sel_hi:[0,1]
	v_pk_mul_f32 v[230:231], v[216:217], v[204:205] op_sel:[1,0]
	ds_read_b64 v[26:27], v3 offset:41216
	v_pk_mul_f32 v[224:225], v[216:217], v[206:207] op_sel_hi:[0,1]
	v_pk_mul_f32 v[234:235], v[216:217], v[206:207] op_sel:[1,0]
	ds_read_b128 v[12:15], v2 offset:256
	v_add_f32_e32 v172, v164, v165
	v_add_f32_e32 v174, v166, v167
	ds_read_b128 v[28:31], v2 offset:272
	v_pk_fma_f32 v[218:219], v[72:73], v[184:185], v[218:219]
	v_pk_fma_f32 v[226:227], v[80:81], v[184:185], v[226:227]
	ds_read_b128 v[32:35], v2 offset:8448
	v_pk_fma_f32 v[220:221], v[74:75], v[186:187], v[220:221]
	v_pk_fma_f32 v[228:229], v[82:83], v[186:187], v[228:229]
	ds_read_b128 v[36:39], v2 offset:8464
	v_add_f32_dpp v172, v172, v172 quad_perm:[1,0,3,2] row_mask:0xf bank_mask:0xf bound_ctrl:1
	v_add_f32_dpp v174, v174, v174 quad_perm:[1,0,3,2] row_mask:0xf bank_mask:0xf bound_ctrl:1
	v_pk_fma_f32 v[222:223], v[76:77], v[188:189], v[222:223]
	v_pk_fma_f32 v[230:231], v[84:85], v[188:189], v[230:231]
	v_pk_fma_f32 v[224:225], v[78:79], v[190:191], v[224:225]
	v_pk_fma_f32 v[234:235], v[86:87], v[190:191], v[234:235]
	v_add_f32_dpp v172, v172, v172 quad_perm:[2,3,0,1] row_mask:0xf bank_mask:0xf bound_ctrl:1
	v_add_f32_dpp v174, v174, v174 quad_perm:[2,3,0,1] row_mask:0xf bank_mask:0xf bound_ctrl:1
	s_nop 0
	v_add_f32_dpp v172, v172, v172 row_half_mirror row_mask:0xf bank_mask:0xf bound_ctrl:1
	v_add_f32_dpp v174, v174, v174 row_half_mirror row_mask:0xf bank_mask:0xf bound_ctrl:1
	v_pk_fma_f32 v[72:73], v[192:193], v[172:173], v[218:219] op_sel_hi:[1,0,1]
	v_pk_fma_f32 v[80:81], v[192:193], v[174:175], v[226:227] op_sel_hi:[1,0,1]
	v_pk_fma_f32 v[74:75], v[194:195], v[172:173], v[220:221] op_sel_hi:[1,0,1]
	v_pk_fma_f32 v[82:83], v[194:195], v[174:175], v[228:229] op_sel_hi:[1,0,1]
	v_pk_fma_f32 v[76:77], v[196:197], v[172:173], v[222:223] op_sel_hi:[1,0,1]
	v_pk_fma_f32 v[84:85], v[196:197], v[174:175], v[230:231] op_sel_hi:[1,0,1]
	v_pk_fma_f32 v[78:79], v[198:199], v[172:173], v[224:225] op_sel_hi:[1,0,1]
	v_pk_fma_f32 v[86:87], v[198:199], v[174:175], v[234:235] op_sel_hi:[1,0,1]
	s_waitcnt lgkmcnt(0)
	v_pk_mul_f32 v[164:165], v[72:73], v[4:5]
	v_pk_mul_f32 v[166:167], v[80:81], v[4:5]
	ds_read_b128 v[48:51], v2 offset:16640
	v_pk_mul_f32 v[168:169], v[72:73], v[208:209]
	v_pk_mul_f32 v[170:171], v[80:81], v[208:209]
	ds_read_b128 v[52:55], v2 offset:16656
	v_pk_fma_f32 v[164:165], v[74:75], v[6:7], v[164:165]
	v_pk_fma_f32 v[166:167], v[82:83], v[6:7], v[166:167]
	ds_read_b128 v[176:179], v2 offset:4608
	v_pk_fma_f32 v[168:169], v[74:75], v[210:211], v[168:169]
	v_pk_fma_f32 v[170:171], v[82:83], v[210:211], v[170:171]
	ds_read_b128 v[180:183], v2 offset:4624
	v_pk_fma_f32 v[164:165], v[76:77], v[8:9], v[164:165]
	v_pk_fma_f32 v[166:167], v[84:85], v[8:9], v[166:167]
	ds_read_b128 v[200:203], v2 offset:12800
	v_pk_fma_f32 v[168:169], v[76:77], v[212:213], v[168:169]
	v_pk_fma_f32 v[170:171], v[84:85], v[212:213], v[170:171]
	ds_read_b128 v[204:207], v2 offset:12816
	v_pk_fma_f32 v[164:165], v[78:79], v[10:11], v[164:165]
	v_pk_fma_f32 v[166:167], v[86:87], v[10:11], v[166:167]
	ds_read_b64 v[216:217], v3 offset:41472
	v_pk_fma_f32 v[168:169], v[78:79], v[214:215], v[168:169]
	v_pk_fma_f32 v[170:171], v[86:87], v[214:215], v[170:171]
	ds_read_b128 v[184:187], v2 offset:512
	v_pk_mul_f32 v[218:219], v[26:27], v[40:41] op_sel_hi:[0,1]
	v_pk_mul_f32 v[226:227], v[26:27], v[40:41] op_sel:[1,0]
	ds_read_b128 v[188:191], v2 offset:528
	v_pk_mul_f32 v[220:221], v[26:27], v[42:43] op_sel_hi:[0,1]
	v_pk_mul_f32 v[228:229], v[26:27], v[42:43] op_sel:[1,0]
	ds_read_b128 v[192:195], v2 offset:8704
	v_pk_mul_f32 v[222:223], v[26:27], v[44:45] op_sel_hi:[0,1]
	v_pk_mul_f32 v[230:231], v[26:27], v[44:45] op_sel:[1,0]
	ds_read_b128 v[196:199], v2 offset:8720
	v_pk_mul_f32 v[224:225], v[26:27], v[46:47] op_sel_hi:[0,1]
	v_pk_mul_f32 v[234:235], v[26:27], v[46:47] op_sel:[1,0]
	v_add_f32_e32 v172, v164, v165
	v_add_f32_e32 v174, v166, v167
	v_add_f32_e32 v160, v168, v169
	v_add_f32_e32 v161, v170, v171
	v_pk_fma_f32 v[218:219], v[72:73], v[12:13], v[218:219]
	v_pk_fma_f32 v[226:227], v[80:81], v[12:13], v[226:227]
	v_pk_fma_f32 v[220:221], v[74:75], v[14:15], v[220:221]
	v_pk_fma_f32 v[228:229], v[82:83], v[14:15], v[228:229]
	v_add_f32_dpp v172, v172, v172 quad_perm:[1,0,3,2] row_mask:0xf bank_mask:0xf bound_ctrl:1
	v_add_f32_dpp v174, v174, v174 quad_perm:[1,0,3,2] row_mask:0xf bank_mask:0xf bound_ctrl:1
	v_add_f32_dpp v160, v160, v160 quad_perm:[1,0,3,2] row_mask:0xf bank_mask:0xf bound_ctrl:1
	v_add_f32_dpp v161, v161, v161 quad_perm:[1,0,3,2] row_mask:0xf bank_mask:0xf bound_ctrl:1
	v_pk_fma_f32 v[222:223], v[76:77], v[28:29], v[222:223]
	v_pk_fma_f32 v[230:231], v[84:85], v[28:29], v[230:231]
	v_pk_fma_f32 v[224:225], v[78:79], v[30:31], v[224:225]
	v_pk_fma_f32 v[234:235], v[86:87], v[30:31], v[234:235]
	v_add_f32_dpp v172, v172, v172 quad_perm:[2,3,0,1] row_mask:0xf bank_mask:0xf bound_ctrl:1
	v_add_f32_dpp v174, v174, v174 quad_perm:[2,3,0,1] row_mask:0xf bank_mask:0xf bound_ctrl:1
	v_add_f32_dpp v160, v160, v160 quad_perm:[2,3,0,1] row_mask:0xf bank_mask:0xf bound_ctrl:1
	v_add_f32_dpp v161, v161, v161 quad_perm:[2,3,0,1] row_mask:0xf bank_mask:0xf bound_ctrl:1
	v_add_f32_dpp v172, v172, v172 row_half_mirror row_mask:0xf bank_mask:0xf bound_ctrl:1
	v_add_f32_dpp v174, v174, v174 row_half_mirror row_mask:0xf bank_mask:0xf bound_ctrl:1
	v_add_f32_dpp v160, v160, v160 row_half_mirror row_mask:0xf bank_mask:0xf bound_ctrl:1
	v_add_f32_dpp v161, v161, v161 row_half_mirror row_mask:0xf bank_mask:0xf bound_ctrl:1
	v_pk_fma_f32 v[72:73], v[32:33], v[172:173], v[218:219] op_sel_hi:[1,0,1]
	v_pk_fma_f32 v[80:81], v[32:33], v[174:175], v[226:227] op_sel_hi:[1,0,1]
	v_pk_fma_f32 v[74:75], v[34:35], v[172:173], v[220:221] op_sel_hi:[1,0,1]
	v_pk_fma_f32 v[82:83], v[34:35], v[174:175], v[228:229] op_sel_hi:[1,0,1]
	v_pk_fma_f32 v[76:77], v[36:37], v[172:173], v[222:223] op_sel_hi:[1,0,1]
	v_pk_fma_f32 v[84:85], v[36:37], v[174:175], v[230:231] op_sel_hi:[1,0,1]
	v_pk_fma_f32 v[78:79], v[38:39], v[172:173], v[224:225] op_sel_hi:[1,0,1]
	v_pk_fma_f32 v[86:87], v[38:39], v[174:175], v[234:235] op_sel_hi:[1,0,1]
	ds_write_b64 v1, v[160:161] offset:54016
	s_waitcnt lgkmcnt(1)
	v_pk_mul_f32 v[164:165], v[72:73], v[176:177]
	v_pk_mul_f32 v[166:167], v[80:81], v[176:177]
	ds_read_b128 v[208:211], v2 offset:16896
	v_pk_mul_f32 v[168:169], v[72:73], v[48:49]
	v_pk_mul_f32 v[170:171], v[80:81], v[48:49]
	ds_read_b128 v[212:215], v2 offset:16912
	v_pk_fma_f32 v[164:165], v[74:75], v[178:179], v[164:165]
	v_pk_fma_f32 v[166:167], v[82:83], v[178:179], v[166:167]
	ds_read_b128 v[4:7], v2 offset:4864
	v_pk_fma_f32 v[168:169], v[74:75], v[50:51], v[168:169]
	v_pk_fma_f32 v[170:171], v[82:83], v[50:51], v[170:171]
	ds_read_b128 v[8:11], v2 offset:4880
	v_pk_fma_f32 v[164:165], v[76:77], v[180:181], v[164:165]
	v_pk_fma_f32 v[166:167], v[84:85], v[180:181], v[166:167]
	ds_read_b128 v[40:43], v2 offset:13056
	v_pk_fma_f32 v[168:169], v[76:77], v[52:53], v[168:169]
	v_pk_fma_f32 v[170:171], v[84:85], v[52:53], v[170:171]
	ds_read_b128 v[44:47], v2 offset:13072
	v_pk_fma_f32 v[164:165], v[78:79], v[182:183], v[164:165]
	v_pk_fma_f32 v[166:167], v[86:87], v[182:183], v[166:167]
	ds_read_b64 v[26:27], v3 offset:41728
	v_pk_fma_f32 v[168:169], v[78:79], v[54:55], v[168:169]
	v_pk_fma_f32 v[170:171], v[86:87], v[54:55], v[170:171]
	ds_read_b128 v[12:15], v2 offset:768
	v_pk_mul_f32 v[218:219], v[216:217], v[200:201] op_sel_hi:[0,1]
	v_pk_mul_f32 v[226:227], v[216:217], v[200:201] op_sel:[1,0]
	ds_read_b128 v[28:31], v2 offset:784
	v_pk_mul_f32 v[220:221], v[216:217], v[202:203] op_sel_hi:[0,1]
	v_pk_mul_f32 v[228:229], v[216:217], v[202:203] op_sel:[1,0]
	ds_read_b128 v[32:35], v2 offset:8960
	v_pk_mul_f32 v[222:223], v[216:217], v[204:205] op_sel_hi:[0,1]
	v_pk_mul_f32 v[230:231], v[216:217], v[204:205] op_sel:[1,0]
	ds_read_b128 v[36:39], v2 offset:8976
	v_pk_mul_f32 v[224:225], v[216:217], v[206:207] op_sel_hi:[0,1]
	v_pk_mul_f32 v[234:235], v[216:217], v[206:207] op_sel:[1,0]
	v_add_f32_e32 v172, v164, v165
	v_add_f32_e32 v174, v166, v167
	v_add_f32_e32 v160, v168, v169
	v_add_f32_e32 v161, v170, v171
	v_pk_fma_f32 v[218:219], v[72:73], v[184:185], v[218:219]
	v_pk_fma_f32 v[226:227], v[80:81], v[184:185], v[226:227]
	v_pk_fma_f32 v[220:221], v[74:75], v[186:187], v[220:221]
	v_pk_fma_f32 v[228:229], v[82:83], v[186:187], v[228:229]
	v_add_f32_dpp v172, v172, v172 quad_perm:[1,0,3,2] row_mask:0xf bank_mask:0xf bound_ctrl:1
	v_add_f32_dpp v174, v174, v174 quad_perm:[1,0,3,2] row_mask:0xf bank_mask:0xf bound_ctrl:1
	v_add_f32_dpp v160, v160, v160 quad_perm:[1,0,3,2] row_mask:0xf bank_mask:0xf bound_ctrl:1
	v_add_f32_dpp v161, v161, v161 quad_perm:[1,0,3,2] row_mask:0xf bank_mask:0xf bound_ctrl:1
	v_pk_fma_f32 v[222:223], v[76:77], v[188:189], v[222:223]
	v_pk_fma_f32 v[230:231], v[84:85], v[188:189], v[230:231]
	v_pk_fma_f32 v[224:225], v[78:79], v[190:191], v[224:225]
	v_pk_fma_f32 v[234:235], v[86:87], v[190:191], v[234:235]
	v_add_f32_dpp v172, v172, v172 quad_perm:[2,3,0,1] row_mask:0xf bank_mask:0xf bound_ctrl:1
	v_add_f32_dpp v174, v174, v174 quad_perm:[2,3,0,1] row_mask:0xf bank_mask:0xf bound_ctrl:1
	v_add_f32_dpp v160, v160, v160 quad_perm:[2,3,0,1] row_mask:0xf bank_mask:0xf bound_ctrl:1
	v_add_f32_dpp v161, v161, v161 quad_perm:[2,3,0,1] row_mask:0xf bank_mask:0xf bound_ctrl:1
	v_add_f32_dpp v172, v172, v172 row_half_mirror row_mask:0xf bank_mask:0xf bound_ctrl:1
	v_add_f32_dpp v174, v174, v174 row_half_mirror row_mask:0xf bank_mask:0xf bound_ctrl:1
	v_add_f32_dpp v160, v160, v160 row_half_mirror row_mask:0xf bank_mask:0xf bound_ctrl:1
	v_add_f32_dpp v161, v161, v161 row_half_mirror row_mask:0xf bank_mask:0xf bound_ctrl:1
	v_pk_fma_f32 v[72:73], v[192:193], v[172:173], v[218:219] op_sel_hi:[1,0,1]
	v_pk_fma_f32 v[80:81], v[192:193], v[174:175], v[226:227] op_sel_hi:[1,0,1]
	v_pk_fma_f32 v[74:75], v[194:195], v[172:173], v[220:221] op_sel_hi:[1,0,1]
	v_pk_fma_f32 v[82:83], v[194:195], v[174:175], v[228:229] op_sel_hi:[1,0,1]
	v_pk_fma_f32 v[76:77], v[196:197], v[172:173], v[222:223] op_sel_hi:[1,0,1]
	v_pk_fma_f32 v[84:85], v[196:197], v[174:175], v[230:231] op_sel_hi:[1,0,1]
	v_pk_fma_f32 v[78:79], v[198:199], v[172:173], v[224:225] op_sel_hi:[1,0,1]
	v_pk_fma_f32 v[86:87], v[198:199], v[174:175], v[234:235] op_sel_hi:[1,0,1]
	ds_write_b64 v1, v[160:161] offset:54272
	s_waitcnt lgkmcnt(1)
	v_pk_mul_f32 v[164:165], v[72:73], v[4:5]
	v_pk_mul_f32 v[166:167], v[80:81], v[4:5]
	ds_read_b128 v[48:51], v2 offset:17152
	v_pk_mul_f32 v[168:169], v[72:73], v[208:209]
	v_pk_mul_f32 v[170:171], v[80:81], v[208:209]
	ds_read_b128 v[52:55], v2 offset:17168
	v_pk_fma_f32 v[164:165], v[74:75], v[6:7], v[164:165]
	v_pk_fma_f32 v[166:167], v[82:83], v[6:7], v[166:167]
	ds_read_b128 v[176:179], v2 offset:5120
	v_pk_fma_f32 v[168:169], v[74:75], v[210:211], v[168:169]
	v_pk_fma_f32 v[170:171], v[82:83], v[210:211], v[170:171]
	ds_read_b128 v[180:183], v2 offset:5136
	v_pk_fma_f32 v[164:165], v[76:77], v[8:9], v[164:165]
	v_pk_fma_f32 v[166:167], v[84:85], v[8:9], v[166:167]
	ds_read_b128 v[200:203], v2 offset:13312
	v_pk_fma_f32 v[168:169], v[76:77], v[212:213], v[168:169]
	v_pk_fma_f32 v[170:171], v[84:85], v[212:213], v[170:171]
	ds_read_b128 v[204:207], v2 offset:13328
	v_pk_fma_f32 v[164:165], v[78:79], v[10:11], v[164:165]
	v_pk_fma_f32 v[166:167], v[86:87], v[10:11], v[166:167]
	ds_read_b64 v[216:217], v3 offset:41984
	v_pk_fma_f32 v[168:169], v[78:79], v[214:215], v[168:169]
	v_pk_fma_f32 v[170:171], v[86:87], v[214:215], v[170:171]
	ds_read_b128 v[184:187], v2 offset:1024
	v_pk_mul_f32 v[218:219], v[26:27], v[40:41] op_sel_hi:[0,1]
	v_pk_mul_f32 v[226:227], v[26:27], v[40:41] op_sel:[1,0]
	ds_read_b128 v[188:191], v2 offset:1040
	v_pk_mul_f32 v[220:221], v[26:27], v[42:43] op_sel_hi:[0,1]
	v_pk_mul_f32 v[228:229], v[26:27], v[42:43] op_sel:[1,0]
	ds_read_b128 v[192:195], v2 offset:9216
	v_pk_mul_f32 v[222:223], v[26:27], v[44:45] op_sel_hi:[0,1]
	v_pk_mul_f32 v[230:231], v[26:27], v[44:45] op_sel:[1,0]
	ds_read_b128 v[196:199], v2 offset:9232
	v_pk_mul_f32 v[224:225], v[26:27], v[46:47] op_sel_hi:[0,1]
	v_pk_mul_f32 v[234:235], v[26:27], v[46:47] op_sel:[1,0]
	v_add_f32_e32 v172, v164, v165
	v_add_f32_e32 v174, v166, v167
	v_add_f32_e32 v160, v168, v169
	v_add_f32_e32 v161, v170, v171
	v_pk_fma_f32 v[218:219], v[72:73], v[12:13], v[218:219]
	v_pk_fma_f32 v[226:227], v[80:81], v[12:13], v[226:227]
	v_pk_fma_f32 v[220:221], v[74:75], v[14:15], v[220:221]
	v_pk_fma_f32 v[228:229], v[82:83], v[14:15], v[228:229]
	v_add_f32_dpp v172, v172, v172 quad_perm:[1,0,3,2] row_mask:0xf bank_mask:0xf bound_ctrl:1
	v_add_f32_dpp v174, v174, v174 quad_perm:[1,0,3,2] row_mask:0xf bank_mask:0xf bound_ctrl:1
	v_add_f32_dpp v160, v160, v160 quad_perm:[1,0,3,2] row_mask:0xf bank_mask:0xf bound_ctrl:1
	v_add_f32_dpp v161, v161, v161 quad_perm:[1,0,3,2] row_mask:0xf bank_mask:0xf bound_ctrl:1
	v_pk_fma_f32 v[222:223], v[76:77], v[28:29], v[222:223]
	v_pk_fma_f32 v[230:231], v[84:85], v[28:29], v[230:231]
	v_pk_fma_f32 v[224:225], v[78:79], v[30:31], v[224:225]
	v_pk_fma_f32 v[234:235], v[86:87], v[30:31], v[234:235]
	v_add_f32_dpp v172, v172, v172 quad_perm:[2,3,0,1] row_mask:0xf bank_mask:0xf bound_ctrl:1
	v_add_f32_dpp v174, v174, v174 quad_perm:[2,3,0,1] row_mask:0xf bank_mask:0xf bound_ctrl:1
	v_add_f32_dpp v160, v160, v160 quad_perm:[2,3,0,1] row_mask:0xf bank_mask:0xf bound_ctrl:1
	v_add_f32_dpp v161, v161, v161 quad_perm:[2,3,0,1] row_mask:0xf bank_mask:0xf bound_ctrl:1
	v_add_f32_dpp v172, v172, v172 row_half_mirror row_mask:0xf bank_mask:0xf bound_ctrl:1
	v_add_f32_dpp v174, v174, v174 row_half_mirror row_mask:0xf bank_mask:0xf bound_ctrl:1
	v_add_f32_dpp v160, v160, v160 row_half_mirror row_mask:0xf bank_mask:0xf bound_ctrl:1
	v_add_f32_dpp v161, v161, v161 row_half_mirror row_mask:0xf bank_mask:0xf bound_ctrl:1
	v_pk_fma_f32 v[72:73], v[32:33], v[172:173], v[218:219] op_sel_hi:[1,0,1]
	v_pk_fma_f32 v[80:81], v[32:33], v[174:175], v[226:227] op_sel_hi:[1,0,1]
	v_pk_fma_f32 v[74:75], v[34:35], v[172:173], v[220:221] op_sel_hi:[1,0,1]
	v_pk_fma_f32 v[82:83], v[34:35], v[174:175], v[228:229] op_sel_hi:[1,0,1]
	v_pk_fma_f32 v[76:77], v[36:37], v[172:173], v[222:223] op_sel_hi:[1,0,1]
	v_pk_fma_f32 v[84:85], v[36:37], v[174:175], v[230:231] op_sel_hi:[1,0,1]
	v_pk_fma_f32 v[78:79], v[38:39], v[172:173], v[224:225] op_sel_hi:[1,0,1]
	v_pk_fma_f32 v[86:87], v[38:39], v[174:175], v[234:235] op_sel_hi:[1,0,1]
	ds_write_b64 v1, v[160:161] offset:54528
	s_waitcnt lgkmcnt(1)
	v_pk_mul_f32 v[164:165], v[72:73], v[176:177]
	v_pk_mul_f32 v[166:167], v[80:81], v[176:177]
	ds_read_b128 v[208:211], v2 offset:17408
	v_pk_mul_f32 v[168:169], v[72:73], v[48:49]
	v_pk_mul_f32 v[170:171], v[80:81], v[48:49]
	ds_read_b128 v[212:215], v2 offset:17424
	v_pk_fma_f32 v[164:165], v[74:75], v[178:179], v[164:165]
	v_pk_fma_f32 v[166:167], v[82:83], v[178:179], v[166:167]
	ds_read_b128 v[4:7], v2 offset:5376
	v_pk_fma_f32 v[168:169], v[74:75], v[50:51], v[168:169]
	v_pk_fma_f32 v[170:171], v[82:83], v[50:51], v[170:171]
	ds_read_b128 v[8:11], v2 offset:5392
	v_pk_fma_f32 v[164:165], v[76:77], v[180:181], v[164:165]
	v_pk_fma_f32 v[166:167], v[84:85], v[180:181], v[166:167]
	ds_read_b128 v[40:43], v2 offset:13568
	v_pk_fma_f32 v[168:169], v[76:77], v[52:53], v[168:169]
	v_pk_fma_f32 v[170:171], v[84:85], v[52:53], v[170:171]
	ds_read_b128 v[44:47], v2 offset:13584
	v_pk_fma_f32 v[164:165], v[78:79], v[182:183], v[164:165]
	v_pk_fma_f32 v[166:167], v[86:87], v[182:183], v[166:167]
	ds_read_b64 v[26:27], v3 offset:42240
	v_pk_fma_f32 v[168:169], v[78:79], v[54:55], v[168:169]
	v_pk_fma_f32 v[170:171], v[86:87], v[54:55], v[170:171]
	ds_read_b128 v[12:15], v2 offset:1280
	v_pk_mul_f32 v[218:219], v[216:217], v[200:201] op_sel_hi:[0,1]
	v_pk_mul_f32 v[226:227], v[216:217], v[200:201] op_sel:[1,0]
	ds_read_b128 v[28:31], v2 offset:1296
	v_pk_mul_f32 v[220:221], v[216:217], v[202:203] op_sel_hi:[0,1]
	v_pk_mul_f32 v[228:229], v[216:217], v[202:203] op_sel:[1,0]
	ds_read_b128 v[32:35], v2 offset:9472
	v_pk_mul_f32 v[222:223], v[216:217], v[204:205] op_sel_hi:[0,1]
	v_pk_mul_f32 v[230:231], v[216:217], v[204:205] op_sel:[1,0]
	ds_read_b128 v[36:39], v2 offset:9488
	v_pk_mul_f32 v[224:225], v[216:217], v[206:207] op_sel_hi:[0,1]
	v_pk_mul_f32 v[234:235], v[216:217], v[206:207] op_sel:[1,0]
	v_add_f32_e32 v172, v164, v165
	v_add_f32_e32 v174, v166, v167
	v_add_f32_e32 v160, v168, v169
	v_add_f32_e32 v161, v170, v171
	v_pk_fma_f32 v[218:219], v[72:73], v[184:185], v[218:219]
	v_pk_fma_f32 v[226:227], v[80:81], v[184:185], v[226:227]
	v_pk_fma_f32 v[220:221], v[74:75], v[186:187], v[220:221]
	v_pk_fma_f32 v[228:229], v[82:83], v[186:187], v[228:229]
	v_add_f32_dpp v172, v172, v172 quad_perm:[1,0,3,2] row_mask:0xf bank_mask:0xf bound_ctrl:1
	v_add_f32_dpp v174, v174, v174 quad_perm:[1,0,3,2] row_mask:0xf bank_mask:0xf bound_ctrl:1
	v_add_f32_dpp v160, v160, v160 quad_perm:[1,0,3,2] row_mask:0xf bank_mask:0xf bound_ctrl:1
	v_add_f32_dpp v161, v161, v161 quad_perm:[1,0,3,2] row_mask:0xf bank_mask:0xf bound_ctrl:1
	v_pk_fma_f32 v[222:223], v[76:77], v[188:189], v[222:223]
	v_pk_fma_f32 v[230:231], v[84:85], v[188:189], v[230:231]
	v_pk_fma_f32 v[224:225], v[78:79], v[190:191], v[224:225]
	v_pk_fma_f32 v[234:235], v[86:87], v[190:191], v[234:235]
	v_add_f32_dpp v172, v172, v172 quad_perm:[2,3,0,1] row_mask:0xf bank_mask:0xf bound_ctrl:1
	v_add_f32_dpp v174, v174, v174 quad_perm:[2,3,0,1] row_mask:0xf bank_mask:0xf bound_ctrl:1
	v_add_f32_dpp v160, v160, v160 quad_perm:[2,3,0,1] row_mask:0xf bank_mask:0xf bound_ctrl:1
	v_add_f32_dpp v161, v161, v161 quad_perm:[2,3,0,1] row_mask:0xf bank_mask:0xf bound_ctrl:1
	v_add_f32_dpp v172, v172, v172 row_half_mirror row_mask:0xf bank_mask:0xf bound_ctrl:1
	v_add_f32_dpp v174, v174, v174 row_half_mirror row_mask:0xf bank_mask:0xf bound_ctrl:1
	v_add_f32_dpp v160, v160, v160 row_half_mirror row_mask:0xf bank_mask:0xf bound_ctrl:1
	v_add_f32_dpp v161, v161, v161 row_half_mirror row_mask:0xf bank_mask:0xf bound_ctrl:1
	v_pk_fma_f32 v[72:73], v[192:193], v[172:173], v[218:219] op_sel_hi:[1,0,1]
	v_pk_fma_f32 v[80:81], v[192:193], v[174:175], v[226:227] op_sel_hi:[1,0,1]
	v_pk_fma_f32 v[74:75], v[194:195], v[172:173], v[220:221] op_sel_hi:[1,0,1]
	v_pk_fma_f32 v[82:83], v[194:195], v[174:175], v[228:229] op_sel_hi:[1,0,1]
	v_pk_fma_f32 v[76:77], v[196:197], v[172:173], v[222:223] op_sel_hi:[1,0,1]
	v_pk_fma_f32 v[84:85], v[196:197], v[174:175], v[230:231] op_sel_hi:[1,0,1]
	v_pk_fma_f32 v[78:79], v[198:199], v[172:173], v[224:225] op_sel_hi:[1,0,1]
	v_pk_fma_f32 v[86:87], v[198:199], v[174:175], v[234:235] op_sel_hi:[1,0,1]
	ds_write_b64 v1, v[160:161] offset:54784
	s_waitcnt lgkmcnt(1)
	v_pk_mul_f32 v[164:165], v[72:73], v[4:5]
	v_pk_mul_f32 v[166:167], v[80:81], v[4:5]
	ds_read_b128 v[48:51], v2 offset:17664
	v_pk_mul_f32 v[168:169], v[72:73], v[208:209]
	v_pk_mul_f32 v[170:171], v[80:81], v[208:209]
	ds_read_b128 v[52:55], v2 offset:17680
	v_pk_fma_f32 v[164:165], v[74:75], v[6:7], v[164:165]
	v_pk_fma_f32 v[166:167], v[82:83], v[6:7], v[166:167]
	ds_read_b128 v[176:179], v2 offset:5632
	v_pk_fma_f32 v[168:169], v[74:75], v[210:211], v[168:169]
	v_pk_fma_f32 v[170:171], v[82:83], v[210:211], v[170:171]
	ds_read_b128 v[180:183], v2 offset:5648
	v_pk_fma_f32 v[164:165], v[76:77], v[8:9], v[164:165]
	v_pk_fma_f32 v[166:167], v[84:85], v[8:9], v[166:167]
	ds_read_b128 v[200:203], v2 offset:13824
	v_pk_fma_f32 v[168:169], v[76:77], v[212:213], v[168:169]
	v_pk_fma_f32 v[170:171], v[84:85], v[212:213], v[170:171]
	ds_read_b128 v[204:207], v2 offset:13840
	v_pk_fma_f32 v[164:165], v[78:79], v[10:11], v[164:165]
	v_pk_fma_f32 v[166:167], v[86:87], v[10:11], v[166:167]
	ds_read_b64 v[216:217], v3 offset:42496
	v_pk_fma_f32 v[168:169], v[78:79], v[214:215], v[168:169]
	v_pk_fma_f32 v[170:171], v[86:87], v[214:215], v[170:171]
	ds_read_b128 v[184:187], v2 offset:1536
	v_pk_mul_f32 v[218:219], v[26:27], v[40:41] op_sel_hi:[0,1]
	v_pk_mul_f32 v[226:227], v[26:27], v[40:41] op_sel:[1,0]
	ds_read_b128 v[188:191], v2 offset:1552
	v_pk_mul_f32 v[220:221], v[26:27], v[42:43] op_sel_hi:[0,1]
	v_pk_mul_f32 v[228:229], v[26:27], v[42:43] op_sel:[1,0]
	ds_read_b128 v[192:195], v2 offset:9728
	v_pk_mul_f32 v[222:223], v[26:27], v[44:45] op_sel_hi:[0,1]
	v_pk_mul_f32 v[230:231], v[26:27], v[44:45] op_sel:[1,0]
	ds_read_b128 v[196:199], v2 offset:9744
	v_pk_mul_f32 v[224:225], v[26:27], v[46:47] op_sel_hi:[0,1]
	v_pk_mul_f32 v[234:235], v[26:27], v[46:47] op_sel:[1,0]
	v_add_f32_e32 v172, v164, v165
	v_add_f32_e32 v174, v166, v167
	v_add_f32_e32 v160, v168, v169
	v_add_f32_e32 v161, v170, v171
	v_pk_fma_f32 v[218:219], v[72:73], v[12:13], v[218:219]
	v_pk_fma_f32 v[226:227], v[80:81], v[12:13], v[226:227]
	v_pk_fma_f32 v[220:221], v[74:75], v[14:15], v[220:221]
	v_pk_fma_f32 v[228:229], v[82:83], v[14:15], v[228:229]
	v_add_f32_dpp v172, v172, v172 quad_perm:[1,0,3,2] row_mask:0xf bank_mask:0xf bound_ctrl:1
	v_add_f32_dpp v174, v174, v174 quad_perm:[1,0,3,2] row_mask:0xf bank_mask:0xf bound_ctrl:1
	v_add_f32_dpp v160, v160, v160 quad_perm:[1,0,3,2] row_mask:0xf bank_mask:0xf bound_ctrl:1
	v_add_f32_dpp v161, v161, v161 quad_perm:[1,0,3,2] row_mask:0xf bank_mask:0xf bound_ctrl:1
	v_pk_fma_f32 v[222:223], v[76:77], v[28:29], v[222:223]
	v_pk_fma_f32 v[230:231], v[84:85], v[28:29], v[230:231]
	v_pk_fma_f32 v[224:225], v[78:79], v[30:31], v[224:225]
	v_pk_fma_f32 v[234:235], v[86:87], v[30:31], v[234:235]
	v_add_f32_dpp v172, v172, v172 quad_perm:[2,3,0,1] row_mask:0xf bank_mask:0xf bound_ctrl:1
	v_add_f32_dpp v174, v174, v174 quad_perm:[2,3,0,1] row_mask:0xf bank_mask:0xf bound_ctrl:1
	v_add_f32_dpp v160, v160, v160 quad_perm:[2,3,0,1] row_mask:0xf bank_mask:0xf bound_ctrl:1
	v_add_f32_dpp v161, v161, v161 quad_perm:[2,3,0,1] row_mask:0xf bank_mask:0xf bound_ctrl:1
	v_add_f32_dpp v172, v172, v172 row_half_mirror row_mask:0xf bank_mask:0xf bound_ctrl:1
	v_add_f32_dpp v174, v174, v174 row_half_mirror row_mask:0xf bank_mask:0xf bound_ctrl:1
	v_add_f32_dpp v160, v160, v160 row_half_mirror row_mask:0xf bank_mask:0xf bound_ctrl:1
	v_add_f32_dpp v161, v161, v161 row_half_mirror row_mask:0xf bank_mask:0xf bound_ctrl:1
	v_pk_fma_f32 v[72:73], v[32:33], v[172:173], v[218:219] op_sel_hi:[1,0,1]
	v_pk_fma_f32 v[80:81], v[32:33], v[174:175], v[226:227] op_sel_hi:[1,0,1]
	v_pk_fma_f32 v[74:75], v[34:35], v[172:173], v[220:221] op_sel_hi:[1,0,1]
	v_pk_fma_f32 v[82:83], v[34:35], v[174:175], v[228:229] op_sel_hi:[1,0,1]
	v_pk_fma_f32 v[76:77], v[36:37], v[172:173], v[222:223] op_sel_hi:[1,0,1]
	v_pk_fma_f32 v[84:85], v[36:37], v[174:175], v[230:231] op_sel_hi:[1,0,1]
	v_pk_fma_f32 v[78:79], v[38:39], v[172:173], v[224:225] op_sel_hi:[1,0,1]
	v_pk_fma_f32 v[86:87], v[38:39], v[174:175], v[234:235] op_sel_hi:[1,0,1]
	ds_write_b64 v1, v[160:161] offset:55040
	s_waitcnt lgkmcnt(1)
	v_pk_mul_f32 v[164:165], v[72:73], v[176:177]
	v_pk_mul_f32 v[166:167], v[80:81], v[176:177]
	ds_read_b128 v[208:211], v2 offset:17920
	v_pk_mul_f32 v[168:169], v[72:73], v[48:49]
	v_pk_mul_f32 v[170:171], v[80:81], v[48:49]
	ds_read_b128 v[212:215], v2 offset:17936
	v_pk_fma_f32 v[164:165], v[74:75], v[178:179], v[164:165]
	v_pk_fma_f32 v[166:167], v[82:83], v[178:179], v[166:167]
	ds_read_b128 v[4:7], v2 offset:5888
	v_pk_fma_f32 v[168:169], v[74:75], v[50:51], v[168:169]
	v_pk_fma_f32 v[170:171], v[82:83], v[50:51], v[170:171]
	ds_read_b128 v[8:11], v2 offset:5904
	v_pk_fma_f32 v[164:165], v[76:77], v[180:181], v[164:165]
	v_pk_fma_f32 v[166:167], v[84:85], v[180:181], v[166:167]
	ds_read_b128 v[40:43], v2 offset:14080
	v_pk_fma_f32 v[168:169], v[76:77], v[52:53], v[168:169]
	v_pk_fma_f32 v[170:171], v[84:85], v[52:53], v[170:171]
	ds_read_b128 v[44:47], v2 offset:14096
	v_pk_fma_f32 v[164:165], v[78:79], v[182:183], v[164:165]
	v_pk_fma_f32 v[166:167], v[86:87], v[182:183], v[166:167]
	ds_read_b64 v[26:27], v3 offset:42752
	v_pk_fma_f32 v[168:169], v[78:79], v[54:55], v[168:169]
	v_pk_fma_f32 v[170:171], v[86:87], v[54:55], v[170:171]
	ds_read_b128 v[12:15], v2 offset:1792
	v_pk_mul_f32 v[218:219], v[216:217], v[200:201] op_sel_hi:[0,1]
	v_pk_mul_f32 v[226:227], v[216:217], v[200:201] op_sel:[1,0]
	ds_read_b128 v[28:31], v2 offset:1808
	v_pk_mul_f32 v[220:221], v[216:217], v[202:203] op_sel_hi:[0,1]
	v_pk_mul_f32 v[228:229], v[216:217], v[202:203] op_sel:[1,0]
	ds_read_b128 v[32:35], v2 offset:9984
	v_pk_mul_f32 v[222:223], v[216:217], v[204:205] op_sel_hi:[0,1]
	v_pk_mul_f32 v[230:231], v[216:217], v[204:205] op_sel:[1,0]
	ds_read_b128 v[36:39], v2 offset:10000
	v_pk_mul_f32 v[224:225], v[216:217], v[206:207] op_sel_hi:[0,1]
	v_pk_mul_f32 v[234:235], v[216:217], v[206:207] op_sel:[1,0]
	v_add_f32_e32 v172, v164, v165
	v_add_f32_e32 v174, v166, v167
	v_add_f32_e32 v160, v168, v169
	v_add_f32_e32 v161, v170, v171
	v_pk_fma_f32 v[218:219], v[72:73], v[184:185], v[218:219]
	v_pk_fma_f32 v[226:227], v[80:81], v[184:185], v[226:227]
	v_pk_fma_f32 v[220:221], v[74:75], v[186:187], v[220:221]
	v_pk_fma_f32 v[228:229], v[82:83], v[186:187], v[228:229]
	v_add_f32_dpp v172, v172, v172 quad_perm:[1,0,3,2] row_mask:0xf bank_mask:0xf bound_ctrl:1
	v_add_f32_dpp v174, v174, v174 quad_perm:[1,0,3,2] row_mask:0xf bank_mask:0xf bound_ctrl:1
	v_add_f32_dpp v160, v160, v160 quad_perm:[1,0,3,2] row_mask:0xf bank_mask:0xf bound_ctrl:1
	v_add_f32_dpp v161, v161, v161 quad_perm:[1,0,3,2] row_mask:0xf bank_mask:0xf bound_ctrl:1
	v_pk_fma_f32 v[222:223], v[76:77], v[188:189], v[222:223]
	v_pk_fma_f32 v[230:231], v[84:85], v[188:189], v[230:231]
	v_pk_fma_f32 v[224:225], v[78:79], v[190:191], v[224:225]
	v_pk_fma_f32 v[234:235], v[86:87], v[190:191], v[234:235]
	v_add_f32_dpp v172, v172, v172 quad_perm:[2,3,0,1] row_mask:0xf bank_mask:0xf bound_ctrl:1
	v_add_f32_dpp v174, v174, v174 quad_perm:[2,3,0,1] row_mask:0xf bank_mask:0xf bound_ctrl:1
	v_add_f32_dpp v160, v160, v160 quad_perm:[2,3,0,1] row_mask:0xf bank_mask:0xf bound_ctrl:1
	v_add_f32_dpp v161, v161, v161 quad_perm:[2,3,0,1] row_mask:0xf bank_mask:0xf bound_ctrl:1
	v_add_f32_dpp v172, v172, v172 row_half_mirror row_mask:0xf bank_mask:0xf bound_ctrl:1
	v_add_f32_dpp v174, v174, v174 row_half_mirror row_mask:0xf bank_mask:0xf bound_ctrl:1
	v_add_f32_dpp v160, v160, v160 row_half_mirror row_mask:0xf bank_mask:0xf bound_ctrl:1
	v_add_f32_dpp v161, v161, v161 row_half_mirror row_mask:0xf bank_mask:0xf bound_ctrl:1
	v_pk_fma_f32 v[72:73], v[192:193], v[172:173], v[218:219] op_sel_hi:[1,0,1]
	v_pk_fma_f32 v[80:81], v[192:193], v[174:175], v[226:227] op_sel_hi:[1,0,1]
	v_pk_fma_f32 v[74:75], v[194:195], v[172:173], v[220:221] op_sel_hi:[1,0,1]
	v_pk_fma_f32 v[82:83], v[194:195], v[174:175], v[228:229] op_sel_hi:[1,0,1]
	v_pk_fma_f32 v[76:77], v[196:197], v[172:173], v[222:223] op_sel_hi:[1,0,1]
	v_pk_fma_f32 v[84:85], v[196:197], v[174:175], v[230:231] op_sel_hi:[1,0,1]
	v_pk_fma_f32 v[78:79], v[198:199], v[172:173], v[224:225] op_sel_hi:[1,0,1]
	v_pk_fma_f32 v[86:87], v[198:199], v[174:175], v[234:235] op_sel_hi:[1,0,1]
	ds_write_b64 v1, v[160:161] offset:55296
	s_waitcnt lgkmcnt(1)
	v_pk_mul_f32 v[164:165], v[72:73], v[4:5]
	v_pk_mul_f32 v[166:167], v[80:81], v[4:5]
	ds_read_b128 v[48:51], v2 offset:18176
	v_pk_mul_f32 v[168:169], v[72:73], v[208:209]
	v_pk_mul_f32 v[170:171], v[80:81], v[208:209]
	ds_read_b128 v[52:55], v2 offset:18192
	v_pk_fma_f32 v[164:165], v[74:75], v[6:7], v[164:165]
	v_pk_fma_f32 v[166:167], v[82:83], v[6:7], v[166:167]
	ds_read_b128 v[176:179], v2 offset:6144
	v_pk_fma_f32 v[168:169], v[74:75], v[210:211], v[168:169]
	v_pk_fma_f32 v[170:171], v[82:83], v[210:211], v[170:171]
	ds_read_b128 v[180:183], v2 offset:6160
	v_pk_fma_f32 v[164:165], v[76:77], v[8:9], v[164:165]
	v_pk_fma_f32 v[166:167], v[84:85], v[8:9], v[166:167]
	ds_read_b128 v[200:203], v2 offset:14336
	v_pk_fma_f32 v[168:169], v[76:77], v[212:213], v[168:169]
	v_pk_fma_f32 v[170:171], v[84:85], v[212:213], v[170:171]
	ds_read_b128 v[204:207], v2 offset:14352
	v_pk_fma_f32 v[164:165], v[78:79], v[10:11], v[164:165]
	v_pk_fma_f32 v[166:167], v[86:87], v[10:11], v[166:167]
	ds_read_b64 v[216:217], v3 offset:43008
	v_pk_fma_f32 v[168:169], v[78:79], v[214:215], v[168:169]
	v_pk_fma_f32 v[170:171], v[86:87], v[214:215], v[170:171]
	ds_read_b128 v[184:187], v2 offset:2048
	v_pk_mul_f32 v[218:219], v[26:27], v[40:41] op_sel_hi:[0,1]
	v_pk_mul_f32 v[226:227], v[26:27], v[40:41] op_sel:[1,0]
	ds_read_b128 v[188:191], v2 offset:2064
	v_pk_mul_f32 v[220:221], v[26:27], v[42:43] op_sel_hi:[0,1]
	v_pk_mul_f32 v[228:229], v[26:27], v[42:43] op_sel:[1,0]
	ds_read_b128 v[192:195], v2 offset:10240
	v_pk_mul_f32 v[222:223], v[26:27], v[44:45] op_sel_hi:[0,1]
	v_pk_mul_f32 v[230:231], v[26:27], v[44:45] op_sel:[1,0]
	ds_read_b128 v[196:199], v2 offset:10256
	v_pk_mul_f32 v[224:225], v[26:27], v[46:47] op_sel_hi:[0,1]
	v_pk_mul_f32 v[234:235], v[26:27], v[46:47] op_sel:[1,0]
	v_add_f32_e32 v172, v164, v165
	v_add_f32_e32 v174, v166, v167
	v_add_f32_e32 v160, v168, v169
	v_add_f32_e32 v161, v170, v171
	v_pk_fma_f32 v[218:219], v[72:73], v[12:13], v[218:219]
	v_pk_fma_f32 v[226:227], v[80:81], v[12:13], v[226:227]
	v_pk_fma_f32 v[220:221], v[74:75], v[14:15], v[220:221]
	v_pk_fma_f32 v[228:229], v[82:83], v[14:15], v[228:229]
	v_add_f32_dpp v172, v172, v172 quad_perm:[1,0,3,2] row_mask:0xf bank_mask:0xf bound_ctrl:1
	v_add_f32_dpp v174, v174, v174 quad_perm:[1,0,3,2] row_mask:0xf bank_mask:0xf bound_ctrl:1
	v_add_f32_dpp v160, v160, v160 quad_perm:[1,0,3,2] row_mask:0xf bank_mask:0xf bound_ctrl:1
	v_add_f32_dpp v161, v161, v161 quad_perm:[1,0,3,2] row_mask:0xf bank_mask:0xf bound_ctrl:1
	v_pk_fma_f32 v[222:223], v[76:77], v[28:29], v[222:223]
	v_pk_fma_f32 v[230:231], v[84:85], v[28:29], v[230:231]
	v_pk_fma_f32 v[224:225], v[78:79], v[30:31], v[224:225]
	v_pk_fma_f32 v[234:235], v[86:87], v[30:31], v[234:235]
	v_add_f32_dpp v172, v172, v172 quad_perm:[2,3,0,1] row_mask:0xf bank_mask:0xf bound_ctrl:1
	v_add_f32_dpp v174, v174, v174 quad_perm:[2,3,0,1] row_mask:0xf bank_mask:0xf bound_ctrl:1
	v_add_f32_dpp v160, v160, v160 quad_perm:[2,3,0,1] row_mask:0xf bank_mask:0xf bound_ctrl:1
	v_add_f32_dpp v161, v161, v161 quad_perm:[2,3,0,1] row_mask:0xf bank_mask:0xf bound_ctrl:1
	v_add_f32_dpp v172, v172, v172 row_half_mirror row_mask:0xf bank_mask:0xf bound_ctrl:1
	v_add_f32_dpp v174, v174, v174 row_half_mirror row_mask:0xf bank_mask:0xf bound_ctrl:1
	v_add_f32_dpp v160, v160, v160 row_half_mirror row_mask:0xf bank_mask:0xf bound_ctrl:1
	v_add_f32_dpp v161, v161, v161 row_half_mirror row_mask:0xf bank_mask:0xf bound_ctrl:1
	v_pk_fma_f32 v[72:73], v[32:33], v[172:173], v[218:219] op_sel_hi:[1,0,1]
	v_pk_fma_f32 v[80:81], v[32:33], v[174:175], v[226:227] op_sel_hi:[1,0,1]
	v_pk_fma_f32 v[74:75], v[34:35], v[172:173], v[220:221] op_sel_hi:[1,0,1]
	v_pk_fma_f32 v[82:83], v[34:35], v[174:175], v[228:229] op_sel_hi:[1,0,1]
	v_pk_fma_f32 v[76:77], v[36:37], v[172:173], v[222:223] op_sel_hi:[1,0,1]
	v_pk_fma_f32 v[84:85], v[36:37], v[174:175], v[230:231] op_sel_hi:[1,0,1]
	v_pk_fma_f32 v[78:79], v[38:39], v[172:173], v[224:225] op_sel_hi:[1,0,1]
	v_pk_fma_f32 v[86:87], v[38:39], v[174:175], v[234:235] op_sel_hi:[1,0,1]
	ds_write_b64 v1, v[160:161] offset:55552
	s_waitcnt lgkmcnt(1)
	v_pk_mul_f32 v[164:165], v[72:73], v[176:177]
	v_pk_mul_f32 v[166:167], v[80:81], v[176:177]
	ds_read_b128 v[208:211], v2 offset:18432
	v_pk_mul_f32 v[168:169], v[72:73], v[48:49]
	v_pk_mul_f32 v[170:171], v[80:81], v[48:49]
	ds_read_b128 v[212:215], v2 offset:18448
	v_pk_fma_f32 v[164:165], v[74:75], v[178:179], v[164:165]
	v_pk_fma_f32 v[166:167], v[82:83], v[178:179], v[166:167]
	ds_read_b128 v[4:7], v2 offset:6400
	v_pk_fma_f32 v[168:169], v[74:75], v[50:51], v[168:169]
	v_pk_fma_f32 v[170:171], v[82:83], v[50:51], v[170:171]
	ds_read_b128 v[8:11], v2 offset:6416
	v_pk_fma_f32 v[164:165], v[76:77], v[180:181], v[164:165]
	v_pk_fma_f32 v[166:167], v[84:85], v[180:181], v[166:167]
	ds_read_b128 v[40:43], v2 offset:14592
	v_pk_fma_f32 v[168:169], v[76:77], v[52:53], v[168:169]
	v_pk_fma_f32 v[170:171], v[84:85], v[52:53], v[170:171]
	ds_read_b128 v[44:47], v2 offset:14608
	v_pk_fma_f32 v[164:165], v[78:79], v[182:183], v[164:165]
	v_pk_fma_f32 v[166:167], v[86:87], v[182:183], v[166:167]
	ds_read_b64 v[26:27], v3 offset:43264
	v_pk_fma_f32 v[168:169], v[78:79], v[54:55], v[168:169]
	v_pk_fma_f32 v[170:171], v[86:87], v[54:55], v[170:171]
	ds_read_b128 v[12:15], v2 offset:2304
	v_pk_mul_f32 v[218:219], v[216:217], v[200:201] op_sel_hi:[0,1]
	v_pk_mul_f32 v[226:227], v[216:217], v[200:201] op_sel:[1,0]
	ds_read_b128 v[28:31], v2 offset:2320
	v_pk_mul_f32 v[220:221], v[216:217], v[202:203] op_sel_hi:[0,1]
	v_pk_mul_f32 v[228:229], v[216:217], v[202:203] op_sel:[1,0]
	ds_read_b128 v[32:35], v2 offset:10496
	v_pk_mul_f32 v[222:223], v[216:217], v[204:205] op_sel_hi:[0,1]
	v_pk_mul_f32 v[230:231], v[216:217], v[204:205] op_sel:[1,0]
	ds_read_b128 v[36:39], v2 offset:10512
	v_pk_mul_f32 v[224:225], v[216:217], v[206:207] op_sel_hi:[0,1]
	v_pk_mul_f32 v[234:235], v[216:217], v[206:207] op_sel:[1,0]
	v_add_f32_e32 v172, v164, v165
	v_add_f32_e32 v174, v166, v167
	v_add_f32_e32 v160, v168, v169
	v_add_f32_e32 v161, v170, v171
	v_pk_fma_f32 v[218:219], v[72:73], v[184:185], v[218:219]
	v_pk_fma_f32 v[226:227], v[80:81], v[184:185], v[226:227]
	v_pk_fma_f32 v[220:221], v[74:75], v[186:187], v[220:221]
	v_pk_fma_f32 v[228:229], v[82:83], v[186:187], v[228:229]
	v_add_f32_dpp v172, v172, v172 quad_perm:[1,0,3,2] row_mask:0xf bank_mask:0xf bound_ctrl:1
	v_add_f32_dpp v174, v174, v174 quad_perm:[1,0,3,2] row_mask:0xf bank_mask:0xf bound_ctrl:1
	v_add_f32_dpp v160, v160, v160 quad_perm:[1,0,3,2] row_mask:0xf bank_mask:0xf bound_ctrl:1
	v_add_f32_dpp v161, v161, v161 quad_perm:[1,0,3,2] row_mask:0xf bank_mask:0xf bound_ctrl:1
	v_pk_fma_f32 v[222:223], v[76:77], v[188:189], v[222:223]
	v_pk_fma_f32 v[230:231], v[84:85], v[188:189], v[230:231]
	v_pk_fma_f32 v[224:225], v[78:79], v[190:191], v[224:225]
	v_pk_fma_f32 v[234:235], v[86:87], v[190:191], v[234:235]
	v_add_f32_dpp v172, v172, v172 quad_perm:[2,3,0,1] row_mask:0xf bank_mask:0xf bound_ctrl:1
	v_add_f32_dpp v174, v174, v174 quad_perm:[2,3,0,1] row_mask:0xf bank_mask:0xf bound_ctrl:1
	v_add_f32_dpp v160, v160, v160 quad_perm:[2,3,0,1] row_mask:0xf bank_mask:0xf bound_ctrl:1
	v_add_f32_dpp v161, v161, v161 quad_perm:[2,3,0,1] row_mask:0xf bank_mask:0xf bound_ctrl:1
	v_add_f32_dpp v172, v172, v172 row_half_mirror row_mask:0xf bank_mask:0xf bound_ctrl:1
	v_add_f32_dpp v174, v174, v174 row_half_mirror row_mask:0xf bank_mask:0xf bound_ctrl:1
	v_add_f32_dpp v160, v160, v160 row_half_mirror row_mask:0xf bank_mask:0xf bound_ctrl:1
	v_add_f32_dpp v161, v161, v161 row_half_mirror row_mask:0xf bank_mask:0xf bound_ctrl:1
	v_pk_fma_f32 v[72:73], v[192:193], v[172:173], v[218:219] op_sel_hi:[1,0,1]
	v_pk_fma_f32 v[80:81], v[192:193], v[174:175], v[226:227] op_sel_hi:[1,0,1]
	v_pk_fma_f32 v[74:75], v[194:195], v[172:173], v[220:221] op_sel_hi:[1,0,1]
	v_pk_fma_f32 v[82:83], v[194:195], v[174:175], v[228:229] op_sel_hi:[1,0,1]
	v_pk_fma_f32 v[76:77], v[196:197], v[172:173], v[222:223] op_sel_hi:[1,0,1]
	v_pk_fma_f32 v[84:85], v[196:197], v[174:175], v[230:231] op_sel_hi:[1,0,1]
	v_pk_fma_f32 v[78:79], v[198:199], v[172:173], v[224:225] op_sel_hi:[1,0,1]
	v_pk_fma_f32 v[86:87], v[198:199], v[174:175], v[234:235] op_sel_hi:[1,0,1]
	ds_write_b64 v1, v[160:161] offset:55808
	s_waitcnt lgkmcnt(1)
	v_pk_mul_f32 v[164:165], v[72:73], v[4:5]
	v_pk_mul_f32 v[166:167], v[80:81], v[4:5]
	ds_read_b128 v[48:51], v2 offset:18688
	v_pk_mul_f32 v[168:169], v[72:73], v[208:209]
	v_pk_mul_f32 v[170:171], v[80:81], v[208:209]
	ds_read_b128 v[52:55], v2 offset:18704
	v_pk_fma_f32 v[164:165], v[74:75], v[6:7], v[164:165]
	v_pk_fma_f32 v[166:167], v[82:83], v[6:7], v[166:167]
	ds_read_b128 v[176:179], v2 offset:6656
	v_pk_fma_f32 v[168:169], v[74:75], v[210:211], v[168:169]
	v_pk_fma_f32 v[170:171], v[82:83], v[210:211], v[170:171]
	ds_read_b128 v[180:183], v2 offset:6672
	v_pk_fma_f32 v[164:165], v[76:77], v[8:9], v[164:165]
	v_pk_fma_f32 v[166:167], v[84:85], v[8:9], v[166:167]
	ds_read_b128 v[200:203], v2 offset:14848
	v_pk_fma_f32 v[168:169], v[76:77], v[212:213], v[168:169]
	v_pk_fma_f32 v[170:171], v[84:85], v[212:213], v[170:171]
	ds_read_b128 v[204:207], v2 offset:14864
	v_pk_fma_f32 v[164:165], v[78:79], v[10:11], v[164:165]
	v_pk_fma_f32 v[166:167], v[86:87], v[10:11], v[166:167]
	ds_read_b64 v[216:217], v3 offset:43520
	v_pk_fma_f32 v[168:169], v[78:79], v[214:215], v[168:169]
	v_pk_fma_f32 v[170:171], v[86:87], v[214:215], v[170:171]
	ds_read_b128 v[184:187], v2 offset:2560
	v_pk_mul_f32 v[218:219], v[26:27], v[40:41] op_sel_hi:[0,1]
	v_pk_mul_f32 v[226:227], v[26:27], v[40:41] op_sel:[1,0]
	ds_read_b128 v[188:191], v2 offset:2576
	v_pk_mul_f32 v[220:221], v[26:27], v[42:43] op_sel_hi:[0,1]
	v_pk_mul_f32 v[228:229], v[26:27], v[42:43] op_sel:[1,0]
	ds_read_b128 v[192:195], v2 offset:10752
	v_pk_mul_f32 v[222:223], v[26:27], v[44:45] op_sel_hi:[0,1]
	v_pk_mul_f32 v[230:231], v[26:27], v[44:45] op_sel:[1,0]
	ds_read_b128 v[196:199], v2 offset:10768
	v_pk_mul_f32 v[224:225], v[26:27], v[46:47] op_sel_hi:[0,1]
	v_pk_mul_f32 v[234:235], v[26:27], v[46:47] op_sel:[1,0]
	v_add_f32_e32 v172, v164, v165
	v_add_f32_e32 v174, v166, v167
	v_add_f32_e32 v160, v168, v169
	v_add_f32_e32 v161, v170, v171
	v_pk_fma_f32 v[218:219], v[72:73], v[12:13], v[218:219]
	v_pk_fma_f32 v[226:227], v[80:81], v[12:13], v[226:227]
	v_pk_fma_f32 v[220:221], v[74:75], v[14:15], v[220:221]
	v_pk_fma_f32 v[228:229], v[82:83], v[14:15], v[228:229]
	v_add_f32_dpp v172, v172, v172 quad_perm:[1,0,3,2] row_mask:0xf bank_mask:0xf bound_ctrl:1
	v_add_f32_dpp v174, v174, v174 quad_perm:[1,0,3,2] row_mask:0xf bank_mask:0xf bound_ctrl:1
	v_add_f32_dpp v160, v160, v160 quad_perm:[1,0,3,2] row_mask:0xf bank_mask:0xf bound_ctrl:1
	v_add_f32_dpp v161, v161, v161 quad_perm:[1,0,3,2] row_mask:0xf bank_mask:0xf bound_ctrl:1
	v_pk_fma_f32 v[222:223], v[76:77], v[28:29], v[222:223]
	v_pk_fma_f32 v[230:231], v[84:85], v[28:29], v[230:231]
	v_pk_fma_f32 v[224:225], v[78:79], v[30:31], v[224:225]
	v_pk_fma_f32 v[234:235], v[86:87], v[30:31], v[234:235]
	v_add_f32_dpp v172, v172, v172 quad_perm:[2,3,0,1] row_mask:0xf bank_mask:0xf bound_ctrl:1
	v_add_f32_dpp v174, v174, v174 quad_perm:[2,3,0,1] row_mask:0xf bank_mask:0xf bound_ctrl:1
	v_add_f32_dpp v160, v160, v160 quad_perm:[2,3,0,1] row_mask:0xf bank_mask:0xf bound_ctrl:1
	v_add_f32_dpp v161, v161, v161 quad_perm:[2,3,0,1] row_mask:0xf bank_mask:0xf bound_ctrl:1
	v_add_f32_dpp v172, v172, v172 row_half_mirror row_mask:0xf bank_mask:0xf bound_ctrl:1
	v_add_f32_dpp v174, v174, v174 row_half_mirror row_mask:0xf bank_mask:0xf bound_ctrl:1
	v_add_f32_dpp v160, v160, v160 row_half_mirror row_mask:0xf bank_mask:0xf bound_ctrl:1
	v_add_f32_dpp v161, v161, v161 row_half_mirror row_mask:0xf bank_mask:0xf bound_ctrl:1
	v_pk_fma_f32 v[72:73], v[32:33], v[172:173], v[218:219] op_sel_hi:[1,0,1]
	v_pk_fma_f32 v[80:81], v[32:33], v[174:175], v[226:227] op_sel_hi:[1,0,1]
	v_pk_fma_f32 v[74:75], v[34:35], v[172:173], v[220:221] op_sel_hi:[1,0,1]
	v_pk_fma_f32 v[82:83], v[34:35], v[174:175], v[228:229] op_sel_hi:[1,0,1]
	v_pk_fma_f32 v[76:77], v[36:37], v[172:173], v[222:223] op_sel_hi:[1,0,1]
	v_pk_fma_f32 v[84:85], v[36:37], v[174:175], v[230:231] op_sel_hi:[1,0,1]
	v_pk_fma_f32 v[78:79], v[38:39], v[172:173], v[224:225] op_sel_hi:[1,0,1]
	v_pk_fma_f32 v[86:87], v[38:39], v[174:175], v[234:235] op_sel_hi:[1,0,1]
	ds_write_b64 v1, v[160:161] offset:56064
	s_waitcnt lgkmcnt(1)
	v_pk_mul_f32 v[164:165], v[72:73], v[176:177]
	v_pk_mul_f32 v[166:167], v[80:81], v[176:177]
	ds_read_b128 v[208:211], v2 offset:18944
	v_pk_mul_f32 v[168:169], v[72:73], v[48:49]
	v_pk_mul_f32 v[170:171], v[80:81], v[48:49]
	ds_read_b128 v[212:215], v2 offset:18960
	v_pk_fma_f32 v[164:165], v[74:75], v[178:179], v[164:165]
	v_pk_fma_f32 v[166:167], v[82:83], v[178:179], v[166:167]
	ds_read_b128 v[4:7], v2 offset:6912
	v_pk_fma_f32 v[168:169], v[74:75], v[50:51], v[168:169]
	v_pk_fma_f32 v[170:171], v[82:83], v[50:51], v[170:171]
	ds_read_b128 v[8:11], v2 offset:6928
	v_pk_fma_f32 v[164:165], v[76:77], v[180:181], v[164:165]
	v_pk_fma_f32 v[166:167], v[84:85], v[180:181], v[166:167]
	ds_read_b128 v[40:43], v2 offset:15104
	v_pk_fma_f32 v[168:169], v[76:77], v[52:53], v[168:169]
	v_pk_fma_f32 v[170:171], v[84:85], v[52:53], v[170:171]
	ds_read_b128 v[44:47], v2 offset:15120
	v_pk_fma_f32 v[164:165], v[78:79], v[182:183], v[164:165]
	v_pk_fma_f32 v[166:167], v[86:87], v[182:183], v[166:167]
	ds_read_b64 v[26:27], v3 offset:43776
	v_pk_fma_f32 v[168:169], v[78:79], v[54:55], v[168:169]
	v_pk_fma_f32 v[170:171], v[86:87], v[54:55], v[170:171]
	ds_read_b128 v[12:15], v2 offset:2816
	v_pk_mul_f32 v[218:219], v[216:217], v[200:201] op_sel_hi:[0,1]
	v_pk_mul_f32 v[226:227], v[216:217], v[200:201] op_sel:[1,0]
	ds_read_b128 v[28:31], v2 offset:2832
	v_pk_mul_f32 v[220:221], v[216:217], v[202:203] op_sel_hi:[0,1]
	v_pk_mul_f32 v[228:229], v[216:217], v[202:203] op_sel:[1,0]
	ds_read_b128 v[32:35], v2 offset:11008
	v_pk_mul_f32 v[222:223], v[216:217], v[204:205] op_sel_hi:[0,1]
	v_pk_mul_f32 v[230:231], v[216:217], v[204:205] op_sel:[1,0]
	ds_read_b128 v[36:39], v2 offset:11024
	v_pk_mul_f32 v[224:225], v[216:217], v[206:207] op_sel_hi:[0,1]
	v_pk_mul_f32 v[234:235], v[216:217], v[206:207] op_sel:[1,0]
	v_add_f32_e32 v172, v164, v165
	v_add_f32_e32 v174, v166, v167
	v_add_f32_e32 v160, v168, v169
	v_add_f32_e32 v161, v170, v171
	v_pk_fma_f32 v[218:219], v[72:73], v[184:185], v[218:219]
	v_pk_fma_f32 v[226:227], v[80:81], v[184:185], v[226:227]
	v_pk_fma_f32 v[220:221], v[74:75], v[186:187], v[220:221]
	v_pk_fma_f32 v[228:229], v[82:83], v[186:187], v[228:229]
	v_add_f32_dpp v172, v172, v172 quad_perm:[1,0,3,2] row_mask:0xf bank_mask:0xf bound_ctrl:1
	v_add_f32_dpp v174, v174, v174 quad_perm:[1,0,3,2] row_mask:0xf bank_mask:0xf bound_ctrl:1
	v_add_f32_dpp v160, v160, v160 quad_perm:[1,0,3,2] row_mask:0xf bank_mask:0xf bound_ctrl:1
	v_add_f32_dpp v161, v161, v161 quad_perm:[1,0,3,2] row_mask:0xf bank_mask:0xf bound_ctrl:1
	v_pk_fma_f32 v[222:223], v[76:77], v[188:189], v[222:223]
	v_pk_fma_f32 v[230:231], v[84:85], v[188:189], v[230:231]
	v_pk_fma_f32 v[224:225], v[78:79], v[190:191], v[224:225]
	v_pk_fma_f32 v[234:235], v[86:87], v[190:191], v[234:235]
	v_add_f32_dpp v172, v172, v172 quad_perm:[2,3,0,1] row_mask:0xf bank_mask:0xf bound_ctrl:1
	v_add_f32_dpp v174, v174, v174 quad_perm:[2,3,0,1] row_mask:0xf bank_mask:0xf bound_ctrl:1
	v_add_f32_dpp v160, v160, v160 quad_perm:[2,3,0,1] row_mask:0xf bank_mask:0xf bound_ctrl:1
	v_add_f32_dpp v161, v161, v161 quad_perm:[2,3,0,1] row_mask:0xf bank_mask:0xf bound_ctrl:1
	v_add_f32_dpp v172, v172, v172 row_half_mirror row_mask:0xf bank_mask:0xf bound_ctrl:1
	v_add_f32_dpp v174, v174, v174 row_half_mirror row_mask:0xf bank_mask:0xf bound_ctrl:1
	v_add_f32_dpp v160, v160, v160 row_half_mirror row_mask:0xf bank_mask:0xf bound_ctrl:1
	v_add_f32_dpp v161, v161, v161 row_half_mirror row_mask:0xf bank_mask:0xf bound_ctrl:1
	v_pk_fma_f32 v[72:73], v[192:193], v[172:173], v[218:219] op_sel_hi:[1,0,1]
	v_pk_fma_f32 v[80:81], v[192:193], v[174:175], v[226:227] op_sel_hi:[1,0,1]
	v_pk_fma_f32 v[74:75], v[194:195], v[172:173], v[220:221] op_sel_hi:[1,0,1]
	v_pk_fma_f32 v[82:83], v[194:195], v[174:175], v[228:229] op_sel_hi:[1,0,1]
	v_pk_fma_f32 v[76:77], v[196:197], v[172:173], v[222:223] op_sel_hi:[1,0,1]
	v_pk_fma_f32 v[84:85], v[196:197], v[174:175], v[230:231] op_sel_hi:[1,0,1]
	v_pk_fma_f32 v[78:79], v[198:199], v[172:173], v[224:225] op_sel_hi:[1,0,1]
	v_pk_fma_f32 v[86:87], v[198:199], v[174:175], v[234:235] op_sel_hi:[1,0,1]
	ds_write_b64 v1, v[160:161] offset:56320
	s_waitcnt lgkmcnt(1)
	v_pk_mul_f32 v[164:165], v[72:73], v[4:5]
	v_pk_mul_f32 v[166:167], v[80:81], v[4:5]
	ds_read_b128 v[48:51], v2 offset:19200
	v_pk_mul_f32 v[168:169], v[72:73], v[208:209]
	v_pk_mul_f32 v[170:171], v[80:81], v[208:209]
	ds_read_b128 v[52:55], v2 offset:19216
	v_pk_fma_f32 v[164:165], v[74:75], v[6:7], v[164:165]
	v_pk_fma_f32 v[166:167], v[82:83], v[6:7], v[166:167]
	ds_read_b128 v[176:179], v2 offset:7168
	v_pk_fma_f32 v[168:169], v[74:75], v[210:211], v[168:169]
	v_pk_fma_f32 v[170:171], v[82:83], v[210:211], v[170:171]
	ds_read_b128 v[180:183], v2 offset:7184
	v_pk_fma_f32 v[164:165], v[76:77], v[8:9], v[164:165]
	v_pk_fma_f32 v[166:167], v[84:85], v[8:9], v[166:167]
	ds_read_b128 v[200:203], v2 offset:15360
	v_pk_fma_f32 v[168:169], v[76:77], v[212:213], v[168:169]
	v_pk_fma_f32 v[170:171], v[84:85], v[212:213], v[170:171]
	ds_read_b128 v[204:207], v2 offset:15376
	v_pk_fma_f32 v[164:165], v[78:79], v[10:11], v[164:165]
	v_pk_fma_f32 v[166:167], v[86:87], v[10:11], v[166:167]
	ds_read_b64 v[216:217], v3 offset:44032
	v_pk_fma_f32 v[168:169], v[78:79], v[214:215], v[168:169]
	v_pk_fma_f32 v[170:171], v[86:87], v[214:215], v[170:171]
	ds_read_b128 v[184:187], v2 offset:3072
	v_pk_mul_f32 v[218:219], v[26:27], v[40:41] op_sel_hi:[0,1]
	v_pk_mul_f32 v[226:227], v[26:27], v[40:41] op_sel:[1,0]
	ds_read_b128 v[188:191], v2 offset:3088
	v_pk_mul_f32 v[220:221], v[26:27], v[42:43] op_sel_hi:[0,1]
	v_pk_mul_f32 v[228:229], v[26:27], v[42:43] op_sel:[1,0]
	ds_read_b128 v[192:195], v2 offset:11264
	v_pk_mul_f32 v[222:223], v[26:27], v[44:45] op_sel_hi:[0,1]
	v_pk_mul_f32 v[230:231], v[26:27], v[44:45] op_sel:[1,0]
	ds_read_b128 v[196:199], v2 offset:11280
	v_pk_mul_f32 v[224:225], v[26:27], v[46:47] op_sel_hi:[0,1]
	v_pk_mul_f32 v[234:235], v[26:27], v[46:47] op_sel:[1,0]
	v_add_f32_e32 v172, v164, v165
	v_add_f32_e32 v174, v166, v167
	v_add_f32_e32 v160, v168, v169
	v_add_f32_e32 v161, v170, v171
	v_pk_fma_f32 v[218:219], v[72:73], v[12:13], v[218:219]
	v_pk_fma_f32 v[226:227], v[80:81], v[12:13], v[226:227]
	v_pk_fma_f32 v[220:221], v[74:75], v[14:15], v[220:221]
	v_pk_fma_f32 v[228:229], v[82:83], v[14:15], v[228:229]
	v_add_f32_dpp v172, v172, v172 quad_perm:[1,0,3,2] row_mask:0xf bank_mask:0xf bound_ctrl:1
	v_add_f32_dpp v174, v174, v174 quad_perm:[1,0,3,2] row_mask:0xf bank_mask:0xf bound_ctrl:1
	v_add_f32_dpp v160, v160, v160 quad_perm:[1,0,3,2] row_mask:0xf bank_mask:0xf bound_ctrl:1
	v_add_f32_dpp v161, v161, v161 quad_perm:[1,0,3,2] row_mask:0xf bank_mask:0xf bound_ctrl:1
	v_pk_fma_f32 v[222:223], v[76:77], v[28:29], v[222:223]
	v_pk_fma_f32 v[230:231], v[84:85], v[28:29], v[230:231]
	v_pk_fma_f32 v[224:225], v[78:79], v[30:31], v[224:225]
	v_pk_fma_f32 v[234:235], v[86:87], v[30:31], v[234:235]
	v_add_f32_dpp v172, v172, v172 quad_perm:[2,3,0,1] row_mask:0xf bank_mask:0xf bound_ctrl:1
	v_add_f32_dpp v174, v174, v174 quad_perm:[2,3,0,1] row_mask:0xf bank_mask:0xf bound_ctrl:1
	v_add_f32_dpp v160, v160, v160 quad_perm:[2,3,0,1] row_mask:0xf bank_mask:0xf bound_ctrl:1
	v_add_f32_dpp v161, v161, v161 quad_perm:[2,3,0,1] row_mask:0xf bank_mask:0xf bound_ctrl:1
	v_add_f32_dpp v172, v172, v172 row_half_mirror row_mask:0xf bank_mask:0xf bound_ctrl:1
	v_add_f32_dpp v174, v174, v174 row_half_mirror row_mask:0xf bank_mask:0xf bound_ctrl:1
	v_add_f32_dpp v160, v160, v160 row_half_mirror row_mask:0xf bank_mask:0xf bound_ctrl:1
	v_add_f32_dpp v161, v161, v161 row_half_mirror row_mask:0xf bank_mask:0xf bound_ctrl:1
	v_pk_fma_f32 v[72:73], v[32:33], v[172:173], v[218:219] op_sel_hi:[1,0,1]
	v_pk_fma_f32 v[80:81], v[32:33], v[174:175], v[226:227] op_sel_hi:[1,0,1]
	v_pk_fma_f32 v[74:75], v[34:35], v[172:173], v[220:221] op_sel_hi:[1,0,1]
	v_pk_fma_f32 v[82:83], v[34:35], v[174:175], v[228:229] op_sel_hi:[1,0,1]
	v_pk_fma_f32 v[76:77], v[36:37], v[172:173], v[222:223] op_sel_hi:[1,0,1]
	v_pk_fma_f32 v[84:85], v[36:37], v[174:175], v[230:231] op_sel_hi:[1,0,1]
	v_pk_fma_f32 v[78:79], v[38:39], v[172:173], v[224:225] op_sel_hi:[1,0,1]
	v_pk_fma_f32 v[86:87], v[38:39], v[174:175], v[234:235] op_sel_hi:[1,0,1]
	ds_write_b64 v1, v[160:161] offset:56576
	s_waitcnt lgkmcnt(1)
	v_pk_mul_f32 v[164:165], v[72:73], v[176:177]
	v_pk_mul_f32 v[166:167], v[80:81], v[176:177]
	ds_read_b128 v[208:211], v2 offset:19456
	v_pk_mul_f32 v[168:169], v[72:73], v[48:49]
	v_pk_mul_f32 v[170:171], v[80:81], v[48:49]
	ds_read_b128 v[212:215], v2 offset:19472
	v_pk_fma_f32 v[164:165], v[74:75], v[178:179], v[164:165]
	v_pk_fma_f32 v[166:167], v[82:83], v[178:179], v[166:167]
	ds_read_b128 v[4:7], v2 offset:7424
	v_pk_fma_f32 v[168:169], v[74:75], v[50:51], v[168:169]
	v_pk_fma_f32 v[170:171], v[82:83], v[50:51], v[170:171]
	ds_read_b128 v[8:11], v2 offset:7440
	v_pk_fma_f32 v[164:165], v[76:77], v[180:181], v[164:165]
	v_pk_fma_f32 v[166:167], v[84:85], v[180:181], v[166:167]
	ds_read_b128 v[40:43], v2 offset:15616
	v_pk_fma_f32 v[168:169], v[76:77], v[52:53], v[168:169]
	v_pk_fma_f32 v[170:171], v[84:85], v[52:53], v[170:171]
	ds_read_b128 v[44:47], v2 offset:15632
	v_pk_fma_f32 v[164:165], v[78:79], v[182:183], v[164:165]
	v_pk_fma_f32 v[166:167], v[86:87], v[182:183], v[166:167]
	ds_read_b64 v[26:27], v3 offset:44288
	v_pk_fma_f32 v[168:169], v[78:79], v[54:55], v[168:169]
	v_pk_fma_f32 v[170:171], v[86:87], v[54:55], v[170:171]
	ds_read_b128 v[12:15], v2 offset:3328
	v_pk_mul_f32 v[218:219], v[216:217], v[200:201] op_sel_hi:[0,1]
	v_pk_mul_f32 v[226:227], v[216:217], v[200:201] op_sel:[1,0]
	ds_read_b128 v[28:31], v2 offset:3344
	v_pk_mul_f32 v[220:221], v[216:217], v[202:203] op_sel_hi:[0,1]
	v_pk_mul_f32 v[228:229], v[216:217], v[202:203] op_sel:[1,0]
	ds_read_b128 v[32:35], v2 offset:11520
	v_pk_mul_f32 v[222:223], v[216:217], v[204:205] op_sel_hi:[0,1]
	v_pk_mul_f32 v[230:231], v[216:217], v[204:205] op_sel:[1,0]
	ds_read_b128 v[36:39], v2 offset:11536
	v_pk_mul_f32 v[224:225], v[216:217], v[206:207] op_sel_hi:[0,1]
	v_pk_mul_f32 v[234:235], v[216:217], v[206:207] op_sel:[1,0]
	v_add_f32_e32 v172, v164, v165
	v_add_f32_e32 v174, v166, v167
	v_add_f32_e32 v160, v168, v169
	v_add_f32_e32 v161, v170, v171
	v_pk_fma_f32 v[218:219], v[72:73], v[184:185], v[218:219]
	v_pk_fma_f32 v[226:227], v[80:81], v[184:185], v[226:227]
	v_pk_fma_f32 v[220:221], v[74:75], v[186:187], v[220:221]
	v_pk_fma_f32 v[228:229], v[82:83], v[186:187], v[228:229]
	v_add_f32_dpp v172, v172, v172 quad_perm:[1,0,3,2] row_mask:0xf bank_mask:0xf bound_ctrl:1
	v_add_f32_dpp v174, v174, v174 quad_perm:[1,0,3,2] row_mask:0xf bank_mask:0xf bound_ctrl:1
	v_add_f32_dpp v160, v160, v160 quad_perm:[1,0,3,2] row_mask:0xf bank_mask:0xf bound_ctrl:1
	v_add_f32_dpp v161, v161, v161 quad_perm:[1,0,3,2] row_mask:0xf bank_mask:0xf bound_ctrl:1
	v_pk_fma_f32 v[222:223], v[76:77], v[188:189], v[222:223]
	v_pk_fma_f32 v[230:231], v[84:85], v[188:189], v[230:231]
	v_pk_fma_f32 v[224:225], v[78:79], v[190:191], v[224:225]
	v_pk_fma_f32 v[234:235], v[86:87], v[190:191], v[234:235]
	v_add_f32_dpp v172, v172, v172 quad_perm:[2,3,0,1] row_mask:0xf bank_mask:0xf bound_ctrl:1
	v_add_f32_dpp v174, v174, v174 quad_perm:[2,3,0,1] row_mask:0xf bank_mask:0xf bound_ctrl:1
	v_add_f32_dpp v160, v160, v160 quad_perm:[2,3,0,1] row_mask:0xf bank_mask:0xf bound_ctrl:1
	v_add_f32_dpp v161, v161, v161 quad_perm:[2,3,0,1] row_mask:0xf bank_mask:0xf bound_ctrl:1
	v_add_f32_dpp v172, v172, v172 row_half_mirror row_mask:0xf bank_mask:0xf bound_ctrl:1
	v_add_f32_dpp v174, v174, v174 row_half_mirror row_mask:0xf bank_mask:0xf bound_ctrl:1
	v_add_f32_dpp v160, v160, v160 row_half_mirror row_mask:0xf bank_mask:0xf bound_ctrl:1
	v_add_f32_dpp v161, v161, v161 row_half_mirror row_mask:0xf bank_mask:0xf bound_ctrl:1
	v_pk_fma_f32 v[72:73], v[192:193], v[172:173], v[218:219] op_sel_hi:[1,0,1]
	v_pk_fma_f32 v[80:81], v[192:193], v[174:175], v[226:227] op_sel_hi:[1,0,1]
	v_pk_fma_f32 v[74:75], v[194:195], v[172:173], v[220:221] op_sel_hi:[1,0,1]
	v_pk_fma_f32 v[82:83], v[194:195], v[174:175], v[228:229] op_sel_hi:[1,0,1]
	v_pk_fma_f32 v[76:77], v[196:197], v[172:173], v[222:223] op_sel_hi:[1,0,1]
	v_pk_fma_f32 v[84:85], v[196:197], v[174:175], v[230:231] op_sel_hi:[1,0,1]
	v_pk_fma_f32 v[78:79], v[198:199], v[172:173], v[224:225] op_sel_hi:[1,0,1]
	v_pk_fma_f32 v[86:87], v[198:199], v[174:175], v[234:235] op_sel_hi:[1,0,1]
	ds_write_b64 v1, v[160:161] offset:56832
	s_waitcnt lgkmcnt(1)
	v_pk_mul_f32 v[164:165], v[72:73], v[4:5]
	v_pk_mul_f32 v[166:167], v[80:81], v[4:5]
	ds_read_b128 v[48:51], v2 offset:19712
	v_pk_mul_f32 v[168:169], v[72:73], v[208:209]
	v_pk_mul_f32 v[170:171], v[80:81], v[208:209]
	ds_read_b128 v[52:55], v2 offset:19728
	v_pk_fma_f32 v[164:165], v[74:75], v[6:7], v[164:165]
	v_pk_fma_f32 v[166:167], v[82:83], v[6:7], v[166:167]
	ds_read_b128 v[176:179], v2 offset:7680
	v_pk_fma_f32 v[168:169], v[74:75], v[210:211], v[168:169]
	v_pk_fma_f32 v[170:171], v[82:83], v[210:211], v[170:171]
	ds_read_b128 v[180:183], v2 offset:7696
	v_pk_fma_f32 v[164:165], v[76:77], v[8:9], v[164:165]
	v_pk_fma_f32 v[166:167], v[84:85], v[8:9], v[166:167]
	ds_read_b128 v[200:203], v2 offset:15872
	v_pk_fma_f32 v[168:169], v[76:77], v[212:213], v[168:169]
	v_pk_fma_f32 v[170:171], v[84:85], v[212:213], v[170:171]
	ds_read_b128 v[204:207], v2 offset:15888
	v_pk_fma_f32 v[164:165], v[78:79], v[10:11], v[164:165]
	v_pk_fma_f32 v[166:167], v[86:87], v[10:11], v[166:167]
	ds_read_b64 v[216:217], v3 offset:44544
	v_pk_fma_f32 v[168:169], v[78:79], v[214:215], v[168:169]
	v_pk_fma_f32 v[170:171], v[86:87], v[214:215], v[170:171]
	ds_read_b128 v[184:187], v2 offset:3584
	v_pk_mul_f32 v[218:219], v[26:27], v[40:41] op_sel_hi:[0,1]
	v_pk_mul_f32 v[226:227], v[26:27], v[40:41] op_sel:[1,0]
	ds_read_b128 v[188:191], v2 offset:3600
	v_pk_mul_f32 v[220:221], v[26:27], v[42:43] op_sel_hi:[0,1]
	v_pk_mul_f32 v[228:229], v[26:27], v[42:43] op_sel:[1,0]
	ds_read_b128 v[192:195], v2 offset:11776
	v_pk_mul_f32 v[222:223], v[26:27], v[44:45] op_sel_hi:[0,1]
	v_pk_mul_f32 v[230:231], v[26:27], v[44:45] op_sel:[1,0]
	ds_read_b128 v[196:199], v2 offset:11792
	v_pk_mul_f32 v[224:225], v[26:27], v[46:47] op_sel_hi:[0,1]
	v_pk_mul_f32 v[234:235], v[26:27], v[46:47] op_sel:[1,0]
	v_add_f32_e32 v172, v164, v165
	v_add_f32_e32 v174, v166, v167
	v_add_f32_e32 v160, v168, v169
	v_add_f32_e32 v161, v170, v171
	v_pk_fma_f32 v[218:219], v[72:73], v[12:13], v[218:219]
	v_pk_fma_f32 v[226:227], v[80:81], v[12:13], v[226:227]
	v_pk_fma_f32 v[220:221], v[74:75], v[14:15], v[220:221]
	v_pk_fma_f32 v[228:229], v[82:83], v[14:15], v[228:229]
	v_add_f32_dpp v172, v172, v172 quad_perm:[1,0,3,2] row_mask:0xf bank_mask:0xf bound_ctrl:1
	v_add_f32_dpp v174, v174, v174 quad_perm:[1,0,3,2] row_mask:0xf bank_mask:0xf bound_ctrl:1
	v_add_f32_dpp v160, v160, v160 quad_perm:[1,0,3,2] row_mask:0xf bank_mask:0xf bound_ctrl:1
	v_add_f32_dpp v161, v161, v161 quad_perm:[1,0,3,2] row_mask:0xf bank_mask:0xf bound_ctrl:1
	v_pk_fma_f32 v[222:223], v[76:77], v[28:29], v[222:223]
	v_pk_fma_f32 v[230:231], v[84:85], v[28:29], v[230:231]
	v_pk_fma_f32 v[224:225], v[78:79], v[30:31], v[224:225]
	v_pk_fma_f32 v[234:235], v[86:87], v[30:31], v[234:235]
	v_add_f32_dpp v172, v172, v172 quad_perm:[2,3,0,1] row_mask:0xf bank_mask:0xf bound_ctrl:1
	v_add_f32_dpp v174, v174, v174 quad_perm:[2,3,0,1] row_mask:0xf bank_mask:0xf bound_ctrl:1
	v_add_f32_dpp v160, v160, v160 quad_perm:[2,3,0,1] row_mask:0xf bank_mask:0xf bound_ctrl:1
	v_add_f32_dpp v161, v161, v161 quad_perm:[2,3,0,1] row_mask:0xf bank_mask:0xf bound_ctrl:1
	v_add_f32_dpp v172, v172, v172 row_half_mirror row_mask:0xf bank_mask:0xf bound_ctrl:1
	v_add_f32_dpp v174, v174, v174 row_half_mirror row_mask:0xf bank_mask:0xf bound_ctrl:1
	v_add_f32_dpp v160, v160, v160 row_half_mirror row_mask:0xf bank_mask:0xf bound_ctrl:1
	v_add_f32_dpp v161, v161, v161 row_half_mirror row_mask:0xf bank_mask:0xf bound_ctrl:1
	v_pk_fma_f32 v[72:73], v[32:33], v[172:173], v[218:219] op_sel_hi:[1,0,1]
	v_pk_fma_f32 v[80:81], v[32:33], v[174:175], v[226:227] op_sel_hi:[1,0,1]
	v_pk_fma_f32 v[74:75], v[34:35], v[172:173], v[220:221] op_sel_hi:[1,0,1]
	v_pk_fma_f32 v[82:83], v[34:35], v[174:175], v[228:229] op_sel_hi:[1,0,1]
	v_pk_fma_f32 v[76:77], v[36:37], v[172:173], v[222:223] op_sel_hi:[1,0,1]
	v_pk_fma_f32 v[84:85], v[36:37], v[174:175], v[230:231] op_sel_hi:[1,0,1]
	v_pk_fma_f32 v[78:79], v[38:39], v[172:173], v[224:225] op_sel_hi:[1,0,1]
	v_pk_fma_f32 v[86:87], v[38:39], v[174:175], v[234:235] op_sel_hi:[1,0,1]
	ds_write_b64 v1, v[160:161] offset:57088
	s_waitcnt lgkmcnt(1)
	v_pk_mul_f32 v[164:165], v[72:73], v[176:177]
	v_pk_mul_f32 v[166:167], v[80:81], v[176:177]
	ds_read_b128 v[208:211], v2 offset:19968
	v_pk_mul_f32 v[168:169], v[72:73], v[48:49]
	v_pk_mul_f32 v[170:171], v[80:81], v[48:49]
	ds_read_b128 v[212:215], v2 offset:19984
	v_pk_fma_f32 v[164:165], v[74:75], v[178:179], v[164:165]
	v_pk_fma_f32 v[166:167], v[82:83], v[178:179], v[166:167]
	ds_read_b128 v[4:7], v2 offset:7936
	v_pk_fma_f32 v[168:169], v[74:75], v[50:51], v[168:169]
	v_pk_fma_f32 v[170:171], v[82:83], v[50:51], v[170:171]
	ds_read_b128 v[8:11], v2 offset:7952
	v_pk_fma_f32 v[164:165], v[76:77], v[180:181], v[164:165]
	v_pk_fma_f32 v[166:167], v[84:85], v[180:181], v[166:167]
	ds_read_b128 v[40:43], v2 offset:16128
	v_pk_fma_f32 v[168:169], v[76:77], v[52:53], v[168:169]
	v_pk_fma_f32 v[170:171], v[84:85], v[52:53], v[170:171]
	ds_read_b128 v[44:47], v2 offset:16144
	v_pk_fma_f32 v[164:165], v[78:79], v[182:183], v[164:165]
	v_pk_fma_f32 v[166:167], v[86:87], v[182:183], v[166:167]
	ds_read_b64 v[26:27], v3 offset:44800
	v_pk_fma_f32 v[168:169], v[78:79], v[54:55], v[168:169]
	v_pk_fma_f32 v[170:171], v[86:87], v[54:55], v[170:171]
	ds_read_b128 v[12:15], v2 offset:3840
	v_pk_mul_f32 v[218:219], v[216:217], v[200:201] op_sel_hi:[0,1]
	v_pk_mul_f32 v[226:227], v[216:217], v[200:201] op_sel:[1,0]
	ds_read_b128 v[28:31], v2 offset:3856
	v_pk_mul_f32 v[220:221], v[216:217], v[202:203] op_sel_hi:[0,1]
	v_pk_mul_f32 v[228:229], v[216:217], v[202:203] op_sel:[1,0]
	ds_read_b128 v[32:35], v2 offset:12032
	v_pk_mul_f32 v[222:223], v[216:217], v[204:205] op_sel_hi:[0,1]
	v_pk_mul_f32 v[230:231], v[216:217], v[204:205] op_sel:[1,0]
	ds_read_b128 v[36:39], v2 offset:12048
	v_pk_mul_f32 v[224:225], v[216:217], v[206:207] op_sel_hi:[0,1]
	v_pk_mul_f32 v[234:235], v[216:217], v[206:207] op_sel:[1,0]
	v_add_f32_e32 v172, v164, v165
	v_add_f32_e32 v174, v166, v167
	v_add_f32_e32 v160, v168, v169
	v_add_f32_e32 v161, v170, v171
	v_pk_fma_f32 v[218:219], v[72:73], v[184:185], v[218:219]
	v_pk_fma_f32 v[226:227], v[80:81], v[184:185], v[226:227]
	v_pk_fma_f32 v[220:221], v[74:75], v[186:187], v[220:221]
	v_pk_fma_f32 v[228:229], v[82:83], v[186:187], v[228:229]
	v_add_f32_dpp v172, v172, v172 quad_perm:[1,0,3,2] row_mask:0xf bank_mask:0xf bound_ctrl:1
	v_add_f32_dpp v174, v174, v174 quad_perm:[1,0,3,2] row_mask:0xf bank_mask:0xf bound_ctrl:1
	v_add_f32_dpp v160, v160, v160 quad_perm:[1,0,3,2] row_mask:0xf bank_mask:0xf bound_ctrl:1
	v_add_f32_dpp v161, v161, v161 quad_perm:[1,0,3,2] row_mask:0xf bank_mask:0xf bound_ctrl:1
	v_pk_fma_f32 v[222:223], v[76:77], v[188:189], v[222:223]
	v_pk_fma_f32 v[230:231], v[84:85], v[188:189], v[230:231]
	v_pk_fma_f32 v[224:225], v[78:79], v[190:191], v[224:225]
	v_pk_fma_f32 v[234:235], v[86:87], v[190:191], v[234:235]
	v_add_f32_dpp v172, v172, v172 quad_perm:[2,3,0,1] row_mask:0xf bank_mask:0xf bound_ctrl:1
	v_add_f32_dpp v174, v174, v174 quad_perm:[2,3,0,1] row_mask:0xf bank_mask:0xf bound_ctrl:1
	v_add_f32_dpp v160, v160, v160 quad_perm:[2,3,0,1] row_mask:0xf bank_mask:0xf bound_ctrl:1
	v_add_f32_dpp v161, v161, v161 quad_perm:[2,3,0,1] row_mask:0xf bank_mask:0xf bound_ctrl:1
	v_add_f32_dpp v172, v172, v172 row_half_mirror row_mask:0xf bank_mask:0xf bound_ctrl:1
	v_add_f32_dpp v174, v174, v174 row_half_mirror row_mask:0xf bank_mask:0xf bound_ctrl:1
	v_add_f32_dpp v160, v160, v160 row_half_mirror row_mask:0xf bank_mask:0xf bound_ctrl:1
	v_add_f32_dpp v161, v161, v161 row_half_mirror row_mask:0xf bank_mask:0xf bound_ctrl:1
	v_pk_fma_f32 v[72:73], v[192:193], v[172:173], v[218:219] op_sel_hi:[1,0,1]
	v_pk_fma_f32 v[80:81], v[192:193], v[174:175], v[226:227] op_sel_hi:[1,0,1]
	v_pk_fma_f32 v[74:75], v[194:195], v[172:173], v[220:221] op_sel_hi:[1,0,1]
	v_pk_fma_f32 v[82:83], v[194:195], v[174:175], v[228:229] op_sel_hi:[1,0,1]
	v_pk_fma_f32 v[76:77], v[196:197], v[172:173], v[222:223] op_sel_hi:[1,0,1]
	v_pk_fma_f32 v[84:85], v[196:197], v[174:175], v[230:231] op_sel_hi:[1,0,1]
	v_pk_fma_f32 v[78:79], v[198:199], v[172:173], v[224:225] op_sel_hi:[1,0,1]
	v_pk_fma_f32 v[86:87], v[198:199], v[174:175], v[234:235] op_sel_hi:[1,0,1]
	ds_write_b64 v1, v[160:161] offset:57344
	s_waitcnt lgkmcnt(1)
	v_pk_mul_f32 v[164:165], v[72:73], v[4:5]
	v_pk_mul_f32 v[166:167], v[80:81], v[4:5]
	ds_read_b128 v[48:51], v2 offset:20224
	v_pk_mul_f32 v[168:169], v[72:73], v[208:209]
	v_pk_mul_f32 v[170:171], v[80:81], v[208:209]
	ds_read_b128 v[52:55], v2 offset:20240
	v_pk_fma_f32 v[164:165], v[74:75], v[6:7], v[164:165]
	v_pk_fma_f32 v[166:167], v[82:83], v[6:7], v[166:167]
	v_pk_fma_f32 v[168:169], v[74:75], v[210:211], v[168:169]
	v_pk_fma_f32 v[170:171], v[82:83], v[210:211], v[170:171]
	v_pk_fma_f32 v[164:165], v[76:77], v[8:9], v[164:165]
	v_pk_fma_f32 v[166:167], v[84:85], v[8:9], v[166:167]
	v_pk_fma_f32 v[168:169], v[76:77], v[212:213], v[168:169]
	v_pk_fma_f32 v[170:171], v[84:85], v[212:213], v[170:171]
	v_pk_fma_f32 v[164:165], v[78:79], v[10:11], v[164:165]
	v_pk_fma_f32 v[166:167], v[86:87], v[10:11], v[166:167]
	v_pk_fma_f32 v[168:169], v[78:79], v[214:215], v[168:169]
	v_pk_fma_f32 v[170:171], v[86:87], v[214:215], v[170:171]
	v_pk_mul_f32 v[218:219], v[26:27], v[40:41] op_sel_hi:[0,1]
	v_pk_mul_f32 v[226:227], v[26:27], v[40:41] op_sel:[1,0]
	v_pk_mul_f32 v[220:221], v[26:27], v[42:43] op_sel_hi:[0,1]
	v_pk_mul_f32 v[228:229], v[26:27], v[42:43] op_sel:[1,0]
	v_pk_mul_f32 v[222:223], v[26:27], v[44:45] op_sel_hi:[0,1]
	v_pk_mul_f32 v[230:231], v[26:27], v[44:45] op_sel:[1,0]
	v_pk_mul_f32 v[224:225], v[26:27], v[46:47] op_sel_hi:[0,1]
	v_pk_mul_f32 v[234:235], v[26:27], v[46:47] op_sel:[1,0]
	v_add_f32_e32 v172, v164, v165
	v_add_f32_e32 v174, v166, v167
	v_add_f32_e32 v160, v168, v169
	v_add_f32_e32 v161, v170, v171
	v_pk_fma_f32 v[218:219], v[72:73], v[12:13], v[218:219]
	v_pk_fma_f32 v[226:227], v[80:81], v[12:13], v[226:227]
	v_pk_fma_f32 v[220:221], v[74:75], v[14:15], v[220:221]
	v_pk_fma_f32 v[228:229], v[82:83], v[14:15], v[228:229]
	v_add_f32_dpp v172, v172, v172 quad_perm:[1,0,3,2] row_mask:0xf bank_mask:0xf bound_ctrl:1
	v_add_f32_dpp v174, v174, v174 quad_perm:[1,0,3,2] row_mask:0xf bank_mask:0xf bound_ctrl:1
	v_add_f32_dpp v160, v160, v160 quad_perm:[1,0,3,2] row_mask:0xf bank_mask:0xf bound_ctrl:1
	v_add_f32_dpp v161, v161, v161 quad_perm:[1,0,3,2] row_mask:0xf bank_mask:0xf bound_ctrl:1
	v_pk_fma_f32 v[222:223], v[76:77], v[28:29], v[222:223]
	v_pk_fma_f32 v[230:231], v[84:85], v[28:29], v[230:231]
	v_pk_fma_f32 v[224:225], v[78:79], v[30:31], v[224:225]
	v_pk_fma_f32 v[234:235], v[86:87], v[30:31], v[234:235]
	v_add_f32_dpp v172, v172, v172 quad_perm:[2,3,0,1] row_mask:0xf bank_mask:0xf bound_ctrl:1
	v_add_f32_dpp v174, v174, v174 quad_perm:[2,3,0,1] row_mask:0xf bank_mask:0xf bound_ctrl:1
	v_add_f32_dpp v160, v160, v160 quad_perm:[2,3,0,1] row_mask:0xf bank_mask:0xf bound_ctrl:1
	v_add_f32_dpp v161, v161, v161 quad_perm:[2,3,0,1] row_mask:0xf bank_mask:0xf bound_ctrl:1
	v_add_f32_dpp v172, v172, v172 row_half_mirror row_mask:0xf bank_mask:0xf bound_ctrl:1
	v_add_f32_dpp v174, v174, v174 row_half_mirror row_mask:0xf bank_mask:0xf bound_ctrl:1
	v_add_f32_dpp v160, v160, v160 row_half_mirror row_mask:0xf bank_mask:0xf bound_ctrl:1
	v_add_f32_dpp v161, v161, v161 row_half_mirror row_mask:0xf bank_mask:0xf bound_ctrl:1
	v_pk_fma_f32 v[72:73], v[32:33], v[172:173], v[218:219] op_sel_hi:[1,0,1]
	v_pk_fma_f32 v[80:81], v[32:33], v[174:175], v[226:227] op_sel_hi:[1,0,1]
	v_pk_fma_f32 v[74:75], v[34:35], v[172:173], v[220:221] op_sel_hi:[1,0,1]
	v_pk_fma_f32 v[82:83], v[34:35], v[174:175], v[228:229] op_sel_hi:[1,0,1]
	v_pk_fma_f32 v[76:77], v[36:37], v[172:173], v[222:223] op_sel_hi:[1,0,1]
	v_pk_fma_f32 v[84:85], v[36:37], v[174:175], v[230:231] op_sel_hi:[1,0,1]
	v_pk_fma_f32 v[78:79], v[38:39], v[172:173], v[224:225] op_sel_hi:[1,0,1]
	v_pk_fma_f32 v[86:87], v[38:39], v[174:175], v[234:235] op_sel_hi:[1,0,1]
	ds_write_b64 v1, v[160:161] offset:57600
	s_waitcnt lgkmcnt(2)
	v_pk_mul_f32 v[168:169], v[72:73], v[48:49]
	v_pk_mul_f32 v[170:171], v[80:81], v[48:49]
	v_pk_fma_f32 v[168:169], v[74:75], v[50:51], v[168:169]
	v_pk_fma_f32 v[170:171], v[82:83], v[50:51], v[170:171]
	s_waitcnt lgkmcnt(1)
	v_pk_fma_f32 v[168:169], v[76:77], v[52:53], v[168:169]
	v_pk_fma_f32 v[170:171], v[84:85], v[52:53], v[170:171]
	v_pk_fma_f32 v[168:169], v[78:79], v[54:55], v[168:169]
	v_pk_fma_f32 v[170:171], v[86:87], v[54:55], v[170:171]
	v_add_f32_e32 v160, v168, v169
	v_add_f32_e32 v161, v170, v171
	s_nop 0
	v_add_f32_dpp v160, v160, v160 quad_perm:[1,0,3,2] row_mask:0xf bank_mask:0xf bound_ctrl:1
	v_add_f32_dpp v161, v161, v161 quad_perm:[1,0,3,2] row_mask:0xf bank_mask:0xf bound_ctrl:1
	s_nop 0
	v_add_f32_dpp v160, v160, v160 quad_perm:[2,3,0,1] row_mask:0xf bank_mask:0xf bound_ctrl:1
	v_add_f32_dpp v161, v161, v161 quad_perm:[2,3,0,1] row_mask:0xf bank_mask:0xf bound_ctrl:1
	s_nop 0
	v_add_f32_dpp v160, v160, v160 row_half_mirror row_mask:0xf bank_mask:0xf bound_ctrl:1
	v_add_f32_dpp v161, v161, v161 row_half_mirror row_mask:0xf bank_mask:0xf bound_ctrl:1
	ds_write_b64 v1, v[160:161] offset:57856
	s_add_i32 s3, s2, 1
	s_mov_b64 s[36:37], 0
